# P3: S2 forward substitution hand-scheduled (LDS rows prefetched with counted lgkmcnt, packed f32 FMA chains, same arithmetic order)
# speedup vs baseline: 1.0244x; 1.0214x over previous
; #define LAS __attribute__((address_space(3)))
; __device__ __forceinline__ bf16_t f2bf(float f) { return (bf16_t)(pk2(f, 0.f) & 0xffffu); }
; #define LBAR() do { asm volatile("s_waitcnt lgkmcnt(0)" ::: "memory"); __builtin_amdgcn_s_barrier(); asm volatile("" ::: "memory"); } while (0)
; template <int I, int C> __device__ __forceinline__ void s2_load(const LAS float* Ll, f32x4 (&lr)[16]) {
;     if constexpr (4 * C < I) { lr[C] = *(const LAS f32x4*)(Ll + I * 64 + 4 * C); s2_load<I, C + 1>(Ll, lr); }
; }
; template <int I, int C> __device__ __forceinline__ void s2_fma(const f32x4 (&lr)[16], const float (&Xc)[64], float& a0, float& a1, float& a2, float& a3) {
;     if constexpr (4 * C < I) {
;         a0 += lr[C].x * Xc[4 * C];
;         if constexpr (4 * C + 1 < I) a1 += lr[C].y * Xc[4 * C + 1];
;         if constexpr (4 * C + 2 < I) a2 += lr[C].z * Xc[4 * C + 2];
;         if constexpr (4 * C + 3 < I) a3 += lr[C].w * Xc[4 * C + 3];
;         s2_fma<I, C + 1>(lr, Xc, a0, a1, a2, a3);
;     }
; }
; template <int I> __device__ __forceinline__ void s2_row(const LAS float* Ll, float (&Xc)[64], int lane) {
;     if constexpr (I < 64) {
;         float a0 = Ll[I * 64 + lane], a1 = 0.f, a2 = 0.f, a3 = 0.f;
;         f32x4 lr[16];
;         s2_load<I, 0>(Ll, lr);
;         s2_fma<I, 0>(lr, Xc, a0, a1, a2, a3);
;         Xc[I] = -((a0 + a1) + (a2 + a3));
;         asm volatile("" ::: "memory");
;         s2_row<I + 1>(Ll, Xc, lane);
;     }
; }
; __device__ __forceinline__ void prep_task(LAS unsigned char* lds, const PrepP& P, int task, int tid, int lane, int wave) {
;     ...
;     LBAR();
;     if (wave == 0) {
;         float Xc[64];
;         s2_row<0>(Ll, Xc, lane);
; #pragma unroll
;         for (int i = 0; i < 64; ++i) Tl[i * TS + lane] = f2bf(Xc[i]);
;         asm volatile("s_waitcnt lgkmcnt(0)" ::: "memory");
;         Tl[lane * TS + lane] = (bf16_t)0x3F80u;
.LBB0_425:
	s_waitcnt lgkmcnt(2)
	v_add_co_u32_e32 v2, vcc, 0x22408000, v50
	v_add_u32_e32 v0, 0x19400, v58
	s_nop 0
	v_addc_co_u32_e32 v3, vcc, 0, v51, vcc
	global_store_dwordx2 v[2:3], v[48:49], off offset:32
	s_waitcnt lgkmcnt(0)
	s_barrier
	s_and_b64 vcc, exec, s[4:5]
	s_cbranch_vccnz .LBB0_415
	s_waitcnt lgkmcnt(0)
	v_mov_b32_e32 v148, v64
	v_lshl_add_u32 v149, v56, 2, v64
	v_lshl_add_u32 v150, v56, 1, v0
	ds_read2st64_b32 v[4:5], v149 offset0:0 offset1:1
	ds_read_b128 v[12:15], v148 offset:256
	ds_read2st64_b32 v[6:7], v149 offset0:2 offset1:3
	ds_read_b128 v[16:19], v148 offset:512
	ds_read_b128 v[20:23], v148 offset:768
	ds_read2st64_b32 v[8:9], v149 offset0:4 offset1:5
	ds_read_b128 v[24:27], v148 offset:1024
	ds_read_b128 v[28:31], v148 offset:1280
	ds_read_b128 v[32:35], v148 offset:1296
	ds_read2st64_b32 v[10:11], v149 offset0:6 offset1:7
	ds_read_b128 v[36:39], v148 offset:1536
	ds_read_b128 v[128:131], v148 offset:1552
	ds_read_b128 v[132:135], v148 offset:1792
	s_waitcnt lgkmcnt(12)
	v_sub_f32_e32 v64, 0, v4
	ds_read_b128 v[136:139], v148 offset:1808
	s_waitcnt lgkmcnt(12)
	v_fma_f32 v48, v64, v12, v5
	ds_read2st64_b32 v[52:53], v149 offset0:8 offset1:9
	v_sub_f32_e32 v65, 0, v48
	v_cvt_pk_bf16_f32 v3, v64, v65
	ds_write_b16 v150, v3
	ds_write_b16_d16_hi v150, v3 offset:144
	s_waitcnt lgkmcnt(13)
	v_fma_f32 v48, v64, v16, v6
	v_mul_f32_e32 v49, v65, v17
	v_sub_f32_e64 v66, -v48, v49
	s_waitcnt lgkmcnt(12)
	v_fma_f32 v48, v64, v20, v7
	ds_read_b128 v[140:143], v148 offset:2048
	v_mul_f32_e32 v49, v65, v21
	v_mul_f32_e32 v50, v66, v22
	v_add_f32_e32 v1, v48, v49
	v_sub_f32_e64 v67, -v1, v50
	v_cvt_pk_bf16_f32 v3, v66, v67
	ds_write_b16 v150, v3 offset:288
	ds_write_b16_d16_hi v150, v3 offset:432
	s_waitcnt lgkmcnt(13)
	v_fma_f32 v48, v64, v24, v8
	v_mul_f32_e32 v49, v65, v25
	v_pk_mul_f32 v[50:51], v[66:67], v[26:27]
	v_add_f32_e32 v1, v48, v49
	v_add_f32_e32 v2, v50, v51
	v_sub_f32_e64 v68, -v1, v2
	s_waitcnt lgkmcnt(11)
	v_fma_f32 v48, v64, v28, v9
	ds_read_b128 v[144:147], v148 offset:2064
	v_mul_f32_e32 v49, v65, v29
	ds_read_b128 v[156:159], v148 offset:2304
	v_pk_mul_f32 v[50:51], v[66:67], v[30:31]
	v_fma_f32 v48, v68, v32, v48
	v_add_f32_e32 v1, v48, v49
	v_add_f32_e32 v2, v50, v51
	v_sub_f32_e64 v69, -v1, v2
	v_cvt_pk_bf16_f32 v3, v68, v69
	ds_write_b16 v150, v3 offset:576
	ds_write_b16_d16_hi v150, v3 offset:720
	s_waitcnt lgkmcnt(12)
	v_fma_f32 v48, v64, v36, v10
	ds_read_b128 v[160:163], v148 offset:2320
	v_mul_f32_e32 v49, v65, v37
	v_pk_mul_f32 v[50:51], v[66:67], v[38:39]
	v_pk_fma_f32 v[48:49], v[68:69], v[128:129], v[48:49]
	v_add_f32_e32 v1, v48, v49
	v_add_f32_e32 v2, v50, v51
	v_sub_f32_e64 v70, -v1, v2
	s_waitcnt lgkmcnt(11)
	v_fma_f32 v48, v64, v132, v11
	ds_read_b128 v[164:167], v148 offset:2336
	v_mul_f32_e32 v49, v65, v133
	ds_read2st64_b32 v[252:253], v149 offset0:10 offset1:11
	v_pk_mul_f32 v[50:51], v[66:67], v[134:135]
	v_pk_fma_f32 v[48:49], v[68:69], v[136:137], v[48:49]
	v_fma_f32 v50, v70, v138, v50
	v_add_f32_e32 v1, v48, v49
	v_add_f32_e32 v2, v50, v51
	v_sub_f32_e64 v71, -v1, v2
	v_cvt_pk_bf16_f32 v3, v70, v71
	ds_write_b16 v150, v3 offset:864
	ds_write_b16_d16_hi v150, v3 offset:1008
	s_waitcnt lgkmcnt(14)
	s_waitcnt lgkmcnt(11)
	v_fma_f32 v48, v64, v140, v52
	ds_read_b128 v[168:171], v148 offset:2560
	v_mul_f32_e32 v49, v65, v141
	ds_read_b128 v[172:175], v148 offset:2576
	v_pk_mul_f32 v[50:51], v[66:67], v[142:143]
	s_waitcnt lgkmcnt(10)
	v_pk_fma_f32 v[48:49], v[68:69], v[144:145], v[48:49]
	ds_read_b128 v[176:179], v148 offset:2592
	v_pk_fma_f32 v[50:51], v[70:71], v[146:147], v[50:51]
	ds_read_b128 v[180:183], v148 offset:2816
	v_add_f32_e32 v1, v48, v49
	ds_read_b128 v[184:187], v148 offset:2832
	v_add_f32_e32 v2, v50, v51
	v_sub_f32_e64 v72, -v1, v2
	s_waitcnt lgkmcnt(12)
	v_fma_f32 v48, v64, v156, v53
	ds_read_b128 v[188:191], v148 offset:2848
	v_mul_f32_e32 v49, v65, v157
	v_pk_mul_f32 v[50:51], v[66:67], v[158:159]
	s_waitcnt lgkmcnt(9)
	v_pk_fma_f32 v[48:49], v[68:69], v[160:161], v[48:49]
	ds_read2st64_b32 v[4:5], v149 offset0:12 offset1:13
	v_pk_fma_f32 v[50:51], v[70:71], v[162:163], v[50:51]
	ds_read_b128 v[200:203], v148 offset:3072
	v_fma_f32 v48, v72, v164, v48
	ds_read_b128 v[204:207], v148 offset:3088
	v_add_f32_e32 v1, v48, v49
	ds_read_b128 v[208:211], v148 offset:3104
	v_add_f32_e32 v2, v50, v51
	v_sub_f32_e64 v73, -v1, v2
	v_cvt_pk_bf16_f32 v3, v72, v73
	ds_write_b16 v150, v3 offset:1152
	ds_write_b16_d16_hi v150, v3 offset:1296
	s_waitcnt lgkmcnt(14)
	s_waitcnt lgkmcnt(9)
	v_fma_f32 v48, v64, v168, v252
	ds_read_b128 v[212:215], v148 offset:3328
	v_mul_f32_e32 v49, v65, v169
	ds_read_b128 v[216:219], v148 offset:3344
	v_pk_mul_f32 v[50:51], v[66:67], v[170:171]
	ds_read_b128 v[220:223], v148 offset:3360
	v_pk_fma_f32 v[48:49], v[68:69], v[172:173], v[48:49]
	ds_read_b128 v[224:227], v148 offset:3376
	v_pk_fma_f32 v[50:51], v[70:71], v[174:175], v[50:51]
	v_pk_fma_f32 v[48:49], v[72:73], v[176:177], v[48:49]
	v_add_f32_e32 v1, v48, v49
	v_add_f32_e32 v2, v50, v51
	v_sub_f32_e64 v74, -v1, v2
	s_waitcnt lgkmcnt(10)
	v_fma_f32 v48, v64, v180, v253
	ds_read2st64_b32 v[6:7], v149 offset0:14 offset1:15
	v_mul_f32_e32 v49, v65, v181
	ds_read_b128 v[228:231], v148 offset:3584
	v_pk_mul_f32 v[50:51], v[66:67], v[182:183]
	ds_read_b128 v[232:235], v148 offset:3600
	v_pk_fma_f32 v[48:49], v[68:69], v[184:185], v[48:49]
	v_pk_fma_f32 v[50:51], v[70:71], v[186:187], v[50:51]
	v_pk_fma_f32 v[48:49], v[72:73], v[188:189], v[48:49]
	v_fma_f32 v50, v74, v190, v50
	v_add_f32_e32 v1, v48, v49
	v_add_f32_e32 v2, v50, v51
	v_sub_f32_e64 v75, -v1, v2
	v_cvt_pk_bf16_f32 v3, v74, v75
	ds_write_b16 v150, v3 offset:1440
	ds_write_b16_d16_hi v150, v3 offset:1584
	s_waitcnt lgkmcnt(12)
; #define LAS __attribute__((address_space(3)))
; __device__ __forceinline__ bf16_t f2bf(float f) { return (bf16_t)(pk2(f, 0.f) & 0xffffu); }
; template <int I, int C> __device__ __forceinline__ void s2_load(const LAS float* Ll, f32x4 (&lr)[16]) {
;     if constexpr (4 * C < I) { lr[C] = *(const LAS f32x4*)(Ll + I * 64 + 4 * C); s2_load<I, C + 1>(Ll, lr); }
; }
; template <int I, int C> __device__ __forceinline__ void s2_fma(const f32x4 (&lr)[16], const float (&Xc)[64], float& a0, float& a1, float& a2, float& a3) {
;     if constexpr (4 * C < I) {
;         a0 += lr[C].x * Xc[4 * C];
;         if constexpr (4 * C + 1 < I) a1 += lr[C].y * Xc[4 * C + 1];
;         if constexpr (4 * C + 2 < I) a2 += lr[C].z * Xc[4 * C + 2];
;         if constexpr (4 * C + 3 < I) a3 += lr[C].w * Xc[4 * C + 3];
;         s2_fma<I, C + 1>(lr, Xc, a0, a1, a2, a3);
;     }
; }
; template <int I> __device__ __forceinline__ void s2_row(const LAS float* Ll, float (&Xc)[64], int lane) {
;     if constexpr (I < 64) {
;         float a0 = Ll[I * 64 + lane], a1 = 0.f, a2 = 0.f, a3 = 0.f;
;         f32x4 lr[16];
;         s2_load<I, 0>(Ll, lr);
;         s2_fma<I, 0>(lr, Xc, a0, a1, a2, a3);
;         Xc[I] = -((a0 + a1) + (a2 + a3));
;         asm volatile("" ::: "memory");
;         s2_row<I + 1>(Ll, Xc, lane);
;     }
; }
; __device__ __forceinline__ void prep_task(LAS unsigned char* lds, const PrepP& P, int task, int tid, int lane, int wave) {
;     ...
; #pragma unroll
;         for (int i = 0; i < 64; ++i) Tl[i * TS + lane] = f2bf(Xc[i]);
	v_fma_f32 v48, v64, v200, v4
	ds_read_b128 v[236:239], v148 offset:3616
	v_mul_f32_e32 v49, v65, v201
	v_pk_mul_f32 v[50:51], v[66:67], v[202:203]
	v_pk_fma_f32 v[48:49], v[68:69], v[204:205], v[48:49]
	v_pk_fma_f32 v[50:51], v[70:71], v[206:207], v[50:51]
	s_waitcnt lgkmcnt(12)
	v_pk_fma_f32 v[48:49], v[72:73], v[208:209], v[48:49]
	ds_read_b128 v[240:243], v148 offset:3632
	v_pk_fma_f32 v[50:51], v[74:75], v[210:211], v[50:51]
	v_add_f32_e32 v1, v48, v49
	v_add_f32_e32 v2, v50, v51
	v_sub_f32_e64 v76, -v1, v2
	s_waitcnt lgkmcnt(8)
	v_fma_f32 v48, v64, v212, v5
	ds_read_b128 v[244:247], v148 offset:3840
	v_mul_f32_e32 v49, v65, v213
	ds_read_b128 v[248:251], v148 offset:3856
	v_pk_mul_f32 v[50:51], v[66:67], v[214:215]
	ds_read_b128 v[12:15], v148 offset:3872
	v_pk_fma_f32 v[48:49], v[68:69], v[216:217], v[48:49]
	ds_read_b128 v[16:19], v148 offset:3888
	v_pk_fma_f32 v[50:51], v[70:71], v[218:219], v[50:51]
	ds_read2st64_b32 v[8:9], v149 offset0:16 offset1:17
	v_pk_fma_f32 v[48:49], v[72:73], v[220:221], v[48:49]
	v_pk_fma_f32 v[50:51], v[74:75], v[222:223], v[50:51]
	s_waitcnt lgkmcnt(12)
	v_fma_f32 v48, v76, v224, v48
	ds_read_b128 v[20:23], v148 offset:4096
	v_add_f32_e32 v1, v48, v49
	v_add_f32_e32 v2, v50, v51
	v_sub_f32_e64 v77, -v1, v2
	v_cvt_pk_bf16_f32 v3, v76, v77
	ds_write_b16 v150, v3 offset:1728
	ds_write_b16_d16_hi v150, v3 offset:1872
	s_waitcnt lgkmcnt(12)
	v_fma_f32 v48, v64, v228, v6
	ds_read_b128 v[24:27], v148 offset:4112
	v_mul_f32_e32 v49, v65, v229
	v_pk_mul_f32 v[50:51], v[66:67], v[230:231]
	v_pk_fma_f32 v[48:49], v[68:69], v[232:233], v[48:49]
	v_pk_fma_f32 v[50:51], v[70:71], v[234:235], v[50:51]
	s_waitcnt lgkmcnt(9)
	v_pk_fma_f32 v[48:49], v[72:73], v[236:237], v[48:49]
	ds_read_b128 v[28:31], v148 offset:4128
	v_pk_fma_f32 v[50:51], v[74:75], v[238:239], v[50:51]
	ds_read_b128 v[32:35], v148 offset:4144
	v_pk_fma_f32 v[48:49], v[76:77], v[240:241], v[48:49]
	ds_read_b128 v[36:39], v148 offset:4352
	v_add_f32_e32 v1, v48, v49
	ds_read_b128 v[128:131], v148 offset:4368
	v_add_f32_e32 v2, v50, v51
	v_sub_f32_e64 v78, -v1, v2
	s_waitcnt lgkmcnt(10)
	v_fma_f32 v48, v64, v244, v7
	ds_read_b128 v[132:135], v148 offset:4384
	v_mul_f32_e32 v49, v65, v245
	ds_read_b128 v[136:139], v148 offset:4400
	v_pk_mul_f32 v[50:51], v[66:67], v[246:247]
	ds_read_b128 v[140:143], v148 offset:4416
	v_pk_fma_f32 v[48:49], v[68:69], v[248:249], v[48:49]
	v_pk_fma_f32 v[50:51], v[70:71], v[250:251], v[50:51]
	v_pk_fma_f32 v[48:49], v[72:73], v[12:13], v[48:49]
	v_pk_fma_f32 v[50:51], v[74:75], v[14:15], v[50:51]
	s_waitcnt lgkmcnt(12)
	v_pk_fma_f32 v[48:49], v[76:77], v[16:17], v[48:49]
	ds_read2st64_b32 v[10:11], v149 offset0:18 offset1:19
	v_fma_f32 v50, v78, v18, v50
	v_add_f32_e32 v1, v48, v49
	v_add_f32_e32 v2, v50, v51
	v_sub_f32_e64 v79, -v1, v2
	v_cvt_pk_bf16_f32 v3, v78, v79
	ds_write_b16 v150, v3 offset:2016
	ds_write_b16_d16_hi v150, v3 offset:2160
	s_waitcnt lgkmcnt(13)
	v_fma_f32 v48, v64, v20, v8
	v_mul_f32_e32 v49, v65, v21
	v_pk_mul_f32 v[50:51], v[66:67], v[22:23]
	s_waitcnt lgkmcnt(8)
	v_pk_fma_f32 v[48:49], v[68:69], v[24:25], v[48:49]
	ds_read_b128 v[144:147], v148 offset:4608
	v_pk_fma_f32 v[50:51], v[70:71], v[26:27], v[50:51]
	ds_read_b128 v[156:159], v148 offset:4624
	v_pk_fma_f32 v[48:49], v[72:73], v[28:29], v[48:49]
	ds_read_b128 v[160:163], v148 offset:4640
	v_pk_fma_f32 v[50:51], v[74:75], v[30:31], v[50:51]
	ds_read_b128 v[164:167], v148 offset:4656
	v_pk_fma_f32 v[48:49], v[76:77], v[32:33], v[48:49]
	ds_read_b128 v[168:171], v148 offset:4672
	v_pk_fma_f32 v[50:51], v[78:79], v[34:35], v[50:51]
	v_add_f32_e32 v1, v48, v49
	v_add_f32_e32 v2, v50, v51
	v_sub_f32_e64 v80, -v1, v2
	s_waitcnt lgkmcnt(10)
	v_fma_f32 v48, v64, v36, v9
	ds_read_b128 v[172:175], v148 offset:4864
	v_mul_f32_e32 v49, v65, v37
	ds_read_b128 v[176:179], v148 offset:4880
	v_pk_mul_f32 v[50:51], v[66:67], v[38:39]
	ds_read_b128 v[180:183], v148 offset:4896
	v_pk_fma_f32 v[48:49], v[68:69], v[128:129], v[48:49]
	v_pk_fma_f32 v[50:51], v[70:71], v[130:131], v[50:51]
	v_pk_fma_f32 v[48:49], v[72:73], v[132:133], v[48:49]
	v_pk_fma_f32 v[50:51], v[74:75], v[134:135], v[50:51]
	s_waitcnt lgkmcnt(11)
	v_pk_fma_f32 v[48:49], v[76:77], v[136:137], v[48:49]
	ds_read_b128 v[184:187], v148 offset:4912
	v_pk_fma_f32 v[50:51], v[78:79], v[138:139], v[50:51]
	ds_read_b128 v[188:191], v148 offset:4928
	v_fma_f32 v48, v80, v140, v48
	v_add_f32_e32 v1, v48, v49
	v_add_f32_e32 v2, v50, v51
	v_sub_f32_e64 v81, -v1, v2
	v_cvt_pk_bf16_f32 v3, v80, v81
	ds_write_b16 v150, v3 offset:2304
	ds_write_b16_d16_hi v150, v3 offset:2448
	s_waitcnt lgkmcnt(14)
	s_waitcnt lgkmcnt(9)
	v_fma_f32 v48, v64, v144, v10
	ds_read2st64_b32 v[52:53], v149 offset0:20 offset1:21
	v_mul_f32_e32 v49, v65, v145
	ds_read_b128 v[200:203], v148 offset:5120
	v_pk_mul_f32 v[50:51], v[66:67], v[146:147]
	ds_read_b128 v[204:207], v148 offset:5136
	v_pk_fma_f32 v[48:49], v[68:69], v[156:157], v[48:49]
	ds_read_b128 v[208:211], v148 offset:5152
	v_pk_fma_f32 v[50:51], v[70:71], v[158:159], v[50:51]
	v_pk_fma_f32 v[48:49], v[72:73], v[160:161], v[48:49]
	v_pk_fma_f32 v[50:51], v[74:75], v[162:163], v[50:51]
	s_waitcnt lgkmcnt(11)
	v_pk_fma_f32 v[48:49], v[76:77], v[164:165], v[48:49]
	ds_read_b128 v[212:215], v148 offset:5168
	v_pk_fma_f32 v[50:51], v[78:79], v[166:167], v[50:51]
	ds_read_b128 v[216:219], v148 offset:5184
	v_pk_fma_f32 v[48:49], v[80:81], v[168:169], v[48:49]
	v_add_f32_e32 v1, v48, v49
	v_add_f32_e32 v2, v50, v51
	v_sub_f32_e64 v82, -v1, v2
	s_waitcnt lgkmcnt(10)
; #define LAS __attribute__((address_space(3)))
; __device__ __forceinline__ bf16_t f2bf(float f) { return (bf16_t)(pk2(f, 0.f) & 0xffffu); }
; template <int I, int C> __device__ __forceinline__ void s2_load(const LAS float* Ll, f32x4 (&lr)[16]) {
;     if constexpr (4 * C < I) { lr[C] = *(const LAS f32x4*)(Ll + I * 64 + 4 * C); s2_load<I, C + 1>(Ll, lr); }
; }
; template <int I, int C> __device__ __forceinline__ void s2_fma(const f32x4 (&lr)[16], const float (&Xc)[64], float& a0, float& a1, float& a2, float& a3) {
;     if constexpr (4 * C < I) {
;         a0 += lr[C].x * Xc[4 * C];
;         if constexpr (4 * C + 1 < I) a1 += lr[C].y * Xc[4 * C + 1];
;         if constexpr (4 * C + 2 < I) a2 += lr[C].z * Xc[4 * C + 2];
;         if constexpr (4 * C + 3 < I) a3 += lr[C].w * Xc[4 * C + 3];
;         s2_fma<I, C + 1>(lr, Xc, a0, a1, a2, a3);
;     }
; }
; template <int I> __device__ __forceinline__ void s2_row(const LAS float* Ll, float (&Xc)[64], int lane) {
;     if constexpr (I < 64) {
;         float a0 = Ll[I * 64 + lane], a1 = 0.f, a2 = 0.f, a3 = 0.f;
;         f32x4 lr[16];
;         s2_load<I, 0>(Ll, lr);
;         s2_fma<I, 0>(lr, Xc, a0, a1, a2, a3);
;         Xc[I] = -((a0 + a1) + (a2 + a3));
;         asm volatile("" ::: "memory");
;         s2_row<I + 1>(Ll, Xc, lane);
;     }
; }
; __device__ __forceinline__ void prep_task(LAS unsigned char* lds, const PrepP& P, int task, int tid, int lane, int wave) {
;     ...
;     if (wave == 0) {
;         float Xc[64];
;         s2_row<0>(Ll, Xc, lane);
; #pragma unroll
;         for (int i = 0; i < 64; ++i) Tl[i * TS + lane] = f2bf(Xc[i]);
;         asm volatile("s_waitcnt lgkmcnt(0)" ::: "memory");
;         Tl[lane * TS + lane] = (bf16_t)0x3F80u;
	v_fma_f32 v48, v64, v172, v11
	ds_read_b128 v[220:223], v148 offset:5376
	v_mul_f32_e32 v49, v65, v173
	ds_read_b128 v[224:227], v148 offset:5392
	v_pk_mul_f32 v[50:51], v[66:67], v[174:175]
	ds_read_b128 v[228:231], v148 offset:5408
	v_pk_fma_f32 v[48:49], v[68:69], v[176:177], v[48:49]
	v_pk_fma_f32 v[50:51], v[70:71], v[178:179], v[50:51]
	v_pk_fma_f32 v[48:49], v[72:73], v[180:181], v[48:49]
	v_pk_fma_f32 v[50:51], v[74:75], v[182:183], v[50:51]
	s_waitcnt lgkmcnt(11)
	v_pk_fma_f32 v[48:49], v[76:77], v[184:185], v[48:49]
	ds_read_b128 v[232:235], v148 offset:5424
	v_pk_fma_f32 v[50:51], v[78:79], v[186:187], v[50:51]
	ds_read_b128 v[236:239], v148 offset:5440
	v_pk_fma_f32 v[48:49], v[80:81], v[188:189], v[48:49]
	v_fma_f32 v50, v82, v190, v50
	v_add_f32_e32 v1, v48, v49
	v_add_f32_e32 v2, v50, v51
	v_sub_f32_e64 v83, -v1, v2
	v_cvt_pk_bf16_f32 v3, v82, v83
	ds_write_b16 v150, v3 offset:2592
	ds_write_b16_d16_hi v150, v3 offset:2736
	s_waitcnt lgkmcnt(10)
	v_fma_f32 v48, v64, v200, v52
	ds_read_b128 v[240:243], v148 offset:5456
	v_mul_f32_e32 v49, v65, v201
	ds_read2st64_b32 v[252:253], v149 offset0:22 offset1:23
	v_pk_mul_f32 v[50:51], v[66:67], v[202:203]
	ds_read_b128 v[244:247], v148 offset:5632
	v_pk_fma_f32 v[48:49], v[68:69], v[204:205], v[48:49]
	v_pk_fma_f32 v[50:51], v[70:71], v[206:207], v[50:51]
	s_waitcnt lgkmcnt(10)
	v_pk_fma_f32 v[48:49], v[72:73], v[208:209], v[48:49]
	ds_read_b128 v[248:251], v148 offset:5648
	v_pk_fma_f32 v[50:51], v[74:75], v[210:211], v[50:51]
	ds_read_b128 v[12:15], v148 offset:5664
	v_pk_fma_f32 v[48:49], v[76:77], v[212:213], v[48:49]
	ds_read_b128 v[16:19], v148 offset:5680
	v_pk_fma_f32 v[50:51], v[78:79], v[214:215], v[50:51]
	v_pk_fma_f32 v[48:49], v[80:81], v[216:217], v[48:49]
	v_pk_fma_f32 v[50:51], v[82:83], v[218:219], v[50:51]
	v_add_f32_e32 v1, v48, v49
	v_add_f32_e32 v2, v50, v51
	v_sub_f32_e64 v84, -v1, v2
	s_waitcnt lgkmcnt(10)
	v_fma_f32 v48, v64, v220, v53
	ds_read_b128 v[20:23], v148 offset:5696
	v_mul_f32_e32 v49, v65, v221
	ds_read_b128 v[24:27], v148 offset:5712
	v_pk_mul_f32 v[50:51], v[66:67], v[222:223]
	ds_read_b128 v[28:31], v148 offset:5888
	v_pk_fma_f32 v[48:49], v[68:69], v[224:225], v[48:49]
	v_pk_fma_f32 v[50:51], v[70:71], v[226:227], v[50:51]
	v_pk_fma_f32 v[48:49], v[72:73], v[228:229], v[48:49]
	v_pk_fma_f32 v[50:51], v[74:75], v[230:231], v[50:51]
	s_waitcnt lgkmcnt(11)
	v_pk_fma_f32 v[48:49], v[76:77], v[232:233], v[48:49]
	ds_read_b128 v[32:35], v148 offset:5904
	v_pk_fma_f32 v[50:51], v[78:79], v[234:235], v[50:51]
	ds_read_b128 v[36:39], v148 offset:5920
	v_pk_fma_f32 v[48:49], v[80:81], v[236:237], v[48:49]
	v_pk_fma_f32 v[50:51], v[82:83], v[238:239], v[50:51]
	s_waitcnt lgkmcnt(10)
	v_fma_f32 v48, v84, v240, v48
	ds_read_b128 v[128:131], v148 offset:5936
	v_add_f32_e32 v1, v48, v49
	ds_read_b128 v[132:135], v148 offset:5952
	v_add_f32_e32 v2, v50, v51
	ds_read_b128 v[136:139], v148 offset:5968
	v_sub_f32_e64 v85, -v1, v2
	v_cvt_pk_bf16_f32 v3, v84, v85
	ds_write_b16 v150, v3 offset:2880
	ds_write_b16_d16_hi v150, v3 offset:3024
	s_waitcnt lgkmcnt(12)
	v_fma_f32 v48, v64, v244, v252
	ds_read2st64_b32 v[4:5], v149 offset0:24 offset1:25
	v_mul_f32_e32 v49, v65, v245
	v_pk_mul_f32 v[50:51], v[66:67], v[246:247]
	v_pk_fma_f32 v[48:49], v[68:69], v[248:249], v[48:49]
	v_pk_fma_f32 v[50:51], v[70:71], v[250:251], v[50:51]
	s_waitcnt lgkmcnt(10)
	v_pk_fma_f32 v[48:49], v[72:73], v[12:13], v[48:49]
	ds_read_b128 v[140:143], v148 offset:6144
	v_pk_fma_f32 v[50:51], v[74:75], v[14:15], v[50:51]
	ds_read_b128 v[144:147], v148 offset:6160
	v_pk_fma_f32 v[48:49], v[76:77], v[16:17], v[48:49]
	ds_read_b128 v[156:159], v148 offset:6176
	v_pk_fma_f32 v[50:51], v[78:79], v[18:19], v[50:51]
	v_pk_fma_f32 v[48:49], v[80:81], v[20:21], v[48:49]
	v_pk_fma_f32 v[50:51], v[82:83], v[22:23], v[50:51]
	s_waitcnt lgkmcnt(12)
	v_pk_fma_f32 v[48:49], v[84:85], v[24:25], v[48:49]
	ds_read_b128 v[160:163], v148 offset:6192
	v_add_f32_e32 v1, v48, v49
	v_add_f32_e32 v2, v50, v51
	v_sub_f32_e64 v86, -v1, v2
	s_waitcnt lgkmcnt(10)
	v_fma_f32 v48, v64, v28, v253
	ds_read_b128 v[164:167], v148 offset:6208
	v_mul_f32_e32 v49, v65, v29
	ds_read_b128 v[168:171], v148 offset:6224
	v_pk_mul_f32 v[50:51], v[66:67], v[30:31]
	ds_read_b128 v[172:175], v148 offset:6400
	v_pk_fma_f32 v[48:49], v[68:69], v[32:33], v[48:49]
	v_pk_fma_f32 v[50:51], v[70:71], v[34:35], v[50:51]
	v_pk_fma_f32 v[48:49], v[72:73], v[36:37], v[48:49]
	v_pk_fma_f32 v[50:51], v[74:75], v[38:39], v[50:51]
	s_waitcnt lgkmcnt(10)
	v_pk_fma_f32 v[48:49], v[76:77], v[128:129], v[48:49]
	ds_read_b128 v[176:179], v148 offset:6416
	v_pk_fma_f32 v[50:51], v[78:79], v[130:131], v[50:51]
	ds_read_b128 v[180:183], v148 offset:6432
	v_pk_fma_f32 v[48:49], v[80:81], v[132:133], v[48:49]
	ds_read_b128 v[184:187], v148 offset:6448
	v_pk_fma_f32 v[50:51], v[82:83], v[134:135], v[50:51]
	v_pk_fma_f32 v[48:49], v[84:85], v[136:137], v[48:49]
	v_fma_f32 v50, v86, v138, v50
	v_add_f32_e32 v1, v48, v49
	v_add_f32_e32 v2, v50, v51
	v_sub_f32_e64 v87, -v1, v2
	v_cvt_pk_bf16_f32 v3, v86, v87
	ds_write_b16 v150, v3 offset:3168
	ds_write_b16_d16_hi v150, v3 offset:3312
	s_waitcnt lgkmcnt(10)
	v_fma_f32 v48, v64, v140, v4
	ds_read_b128 v[188:191], v148 offset:6464
	v_mul_f32_e32 v49, v65, v141
	ds_read_b128 v[200:203], v148 offset:6480
	v_pk_mul_f32 v[50:51], v[66:67], v[142:143]
	ds_read_b128 v[204:207], v148 offset:6496
	v_pk_fma_f32 v[48:49], v[68:69], v[144:145], v[48:49]
	v_pk_fma_f32 v[50:51], v[70:71], v[146:147], v[50:51]
	s_waitcnt lgkmcnt(10)
; #define LAS __attribute__((address_space(3)))
; __device__ __forceinline__ bf16_t f2bf(float f) { return (bf16_t)(pk2(f, 0.f) & 0xffffu); }
; template <int I, int C> __device__ __forceinline__ void s2_load(const LAS float* Ll, f32x4 (&lr)[16]) {
;     if constexpr (4 * C < I) { lr[C] = *(const LAS f32x4*)(Ll + I * 64 + 4 * C); s2_load<I, C + 1>(Ll, lr); }
; }
; template <int I, int C> __device__ __forceinline__ void s2_fma(const f32x4 (&lr)[16], const float (&Xc)[64], float& a0, float& a1, float& a2, float& a3) {
;     if constexpr (4 * C < I) {
;         a0 += lr[C].x * Xc[4 * C];
;         if constexpr (4 * C + 1 < I) a1 += lr[C].y * Xc[4 * C + 1];
;         if constexpr (4 * C + 2 < I) a2 += lr[C].z * Xc[4 * C + 2];
;         if constexpr (4 * C + 3 < I) a3 += lr[C].w * Xc[4 * C + 3];
;         s2_fma<I, C + 1>(lr, Xc, a0, a1, a2, a3);
;     }
; }
; template <int I> __device__ __forceinline__ void s2_row(const LAS float* Ll, float (&Xc)[64], int lane) {
;     if constexpr (I < 64) {
;         float a0 = Ll[I * 64 + lane], a1 = 0.f, a2 = 0.f, a3 = 0.f;
;         f32x4 lr[16];
;         s2_load<I, 0>(Ll, lr);
;         s2_fma<I, 0>(lr, Xc, a0, a1, a2, a3);
;         Xc[I] = -((a0 + a1) + (a2 + a3));
;         asm volatile("" ::: "memory");
;         s2_row<I + 1>(Ll, Xc, lane);
;     }
; }
; __device__ __forceinline__ void prep_task(LAS unsigned char* lds, const PrepP& P, int task, int tid, int lane, int wave) {
;     ...
;     if (wave == 0) {
;         float Xc[64];
;         s2_row<0>(Ll, Xc, lane);
; #pragma unroll
;         for (int i = 0; i < 64; ++i) Tl[i * TS + lane] = f2bf(Xc[i]);
;         asm volatile("s_waitcnt lgkmcnt(0)" ::: "memory");
;         Tl[lane * TS + lane] = (bf16_t)0x3F80u;
	v_pk_fma_f32 v[48:49], v[72:73], v[156:157], v[48:49]
	ds_read2st64_b32 v[6:7], v149 offset0:26 offset1:27
	v_pk_fma_f32 v[50:51], v[74:75], v[158:159], v[50:51]
	ds_read_b128 v[208:211], v148 offset:6656
	v_pk_fma_f32 v[48:49], v[76:77], v[160:161], v[48:49]
	ds_read_b128 v[212:215], v148 offset:6672
	v_pk_fma_f32 v[50:51], v[78:79], v[162:163], v[50:51]
	v_pk_fma_f32 v[48:49], v[80:81], v[164:165], v[48:49]
	v_pk_fma_f32 v[50:51], v[82:83], v[166:167], v[50:51]
	s_waitcnt lgkmcnt(12)
	v_pk_fma_f32 v[48:49], v[84:85], v[168:169], v[48:49]
	ds_read_b128 v[216:219], v148 offset:6688
	v_pk_fma_f32 v[50:51], v[86:87], v[170:171], v[50:51]
	v_add_f32_e32 v1, v48, v49
	v_add_f32_e32 v2, v50, v51
	v_sub_f32_e64 v88, -v1, v2
	s_waitcnt lgkmcnt(10)
	v_fma_f32 v48, v64, v172, v5
	ds_read_b128 v[220:223], v148 offset:6704
	v_mul_f32_e32 v49, v65, v173
	ds_read_b128 v[224:227], v148 offset:6720
	v_pk_mul_f32 v[50:51], v[66:67], v[174:175]
	ds_read_b128 v[228:231], v148 offset:6736
	v_pk_fma_f32 v[48:49], v[68:69], v[176:177], v[48:49]
	v_pk_fma_f32 v[50:51], v[70:71], v[178:179], v[50:51]
	v_pk_fma_f32 v[48:49], v[72:73], v[180:181], v[48:49]
	v_pk_fma_f32 v[50:51], v[74:75], v[182:183], v[50:51]
	s_waitcnt lgkmcnt(12)
	v_pk_fma_f32 v[48:49], v[76:77], v[184:185], v[48:49]
	ds_read_b128 v[232:235], v148 offset:6752
	v_pk_fma_f32 v[50:51], v[78:79], v[186:187], v[50:51]
	s_waitcnt lgkmcnt(8)
	v_pk_fma_f32 v[48:49], v[80:81], v[188:189], v[48:49]
	ds_read_b128 v[236:239], v148 offset:6912
	v_pk_fma_f32 v[50:51], v[82:83], v[190:191], v[50:51]
	ds_read_b128 v[240:243], v148 offset:6928
	v_pk_fma_f32 v[48:49], v[84:85], v[200:201], v[48:49]
	ds_read_b128 v[244:247], v148 offset:6944
	v_pk_fma_f32 v[50:51], v[86:87], v[202:203], v[50:51]
	ds_read_b128 v[248:251], v148 offset:6960
	v_fma_f32 v48, v88, v204, v48
	ds_read_b128 v[12:15], v148 offset:6976
	v_add_f32_e32 v1, v48, v49
	v_add_f32_e32 v2, v50, v51
	v_sub_f32_e64 v89, -v1, v2
	v_cvt_pk_bf16_f32 v3, v88, v89
	ds_write_b16 v150, v3 offset:3456
	ds_write_b16_d16_hi v150, v3 offset:3600
	s_waitcnt lgkmcnt(12)
	v_fma_f32 v48, v64, v208, v6
	ds_read_b128 v[16:19], v148 offset:6992
	v_mul_f32_e32 v49, v65, v209
	v_pk_mul_f32 v[50:51], v[66:67], v[210:211]
	v_pk_fma_f32 v[48:49], v[68:69], v[212:213], v[48:49]
	v_pk_fma_f32 v[50:51], v[70:71], v[214:215], v[50:51]
	s_waitcnt lgkmcnt(10)
	v_pk_fma_f32 v[48:49], v[72:73], v[216:217], v[48:49]
	ds_read_b128 v[20:23], v148 offset:7008
	v_pk_fma_f32 v[50:51], v[74:75], v[218:219], v[50:51]
	ds_read2st64_b32 v[8:9], v149 offset0:28 offset1:29
	v_pk_fma_f32 v[48:49], v[76:77], v[220:221], v[48:49]
	ds_read_b128 v[24:27], v148 offset:7168
	v_pk_fma_f32 v[50:51], v[78:79], v[222:223], v[50:51]
	v_pk_fma_f32 v[48:49], v[80:81], v[224:225], v[48:49]
	v_pk_fma_f32 v[50:51], v[82:83], v[226:227], v[50:51]
	s_waitcnt lgkmcnt(11)
	v_pk_fma_f32 v[48:49], v[84:85], v[228:229], v[48:49]
	ds_read_b128 v[28:31], v148 offset:7184
	v_pk_fma_f32 v[50:51], v[86:87], v[230:231], v[50:51]
	ds_read_b128 v[32:35], v148 offset:7200
	v_pk_fma_f32 v[48:49], v[88:89], v[232:233], v[48:49]
	v_add_f32_e32 v1, v48, v49
	v_add_f32_e32 v2, v50, v51
	v_sub_f32_e64 v90, -v1, v2
	s_waitcnt lgkmcnt(10)
	v_fma_f32 v48, v64, v236, v7
	ds_read_b128 v[36:39], v148 offset:7216
	v_mul_f32_e32 v49, v65, v237
	ds_read_b128 v[128:131], v148 offset:7232
	v_pk_mul_f32 v[50:51], v[66:67], v[238:239]
	ds_read_b128 v[132:135], v148 offset:7248
	v_pk_fma_f32 v[48:49], v[68:69], v[240:241], v[48:49]
	v_pk_fma_f32 v[50:51], v[70:71], v[242:243], v[50:51]
	v_pk_fma_f32 v[48:49], v[72:73], v[244:245], v[48:49]
	v_pk_fma_f32 v[50:51], v[74:75], v[246:247], v[50:51]
	s_waitcnt lgkmcnt(11)
	v_pk_fma_f32 v[48:49], v[76:77], v[248:249], v[48:49]
	ds_read_b128 v[136:139], v148 offset:7264
	v_pk_fma_f32 v[50:51], v[78:79], v[250:251], v[50:51]
	ds_read_b128 v[140:143], v148 offset:7424
	v_pk_fma_f32 v[48:49], v[80:81], v[12:13], v[48:49]
	v_pk_fma_f32 v[50:51], v[82:83], v[14:15], v[50:51]
	s_waitcnt lgkmcnt(9)
	v_pk_fma_f32 v[48:49], v[84:85], v[16:17], v[48:49]
	ds_read_b128 v[144:147], v148 offset:7440
	v_pk_fma_f32 v[50:51], v[86:87], v[18:19], v[50:51]
	ds_read_b128 v[156:159], v148 offset:7456
	v_pk_fma_f32 v[48:49], v[88:89], v[20:21], v[48:49]
	ds_read_b128 v[160:163], v148 offset:7472
	v_fma_f32 v50, v90, v22, v50
	ds_read_b128 v[164:167], v148 offset:7488
	v_add_f32_e32 v1, v48, v49
	v_add_f32_e32 v2, v50, v51
	v_sub_f32_e64 v91, -v1, v2
	v_cvt_pk_bf16_f32 v3, v90, v91
	ds_write_b16 v150, v3 offset:3744
	ds_write_b16_d16_hi v150, v3 offset:3888
	s_waitcnt lgkmcnt(12)
	v_fma_f32 v48, v64, v24, v8
	ds_read_b128 v[168:171], v148 offset:7504
	v_mul_f32_e32 v49, v65, v25
	v_pk_mul_f32 v[50:51], v[66:67], v[26:27]
	v_pk_fma_f32 v[48:49], v[68:69], v[28:29], v[48:49]
	v_pk_fma_f32 v[50:51], v[70:71], v[30:31], v[50:51]
	s_waitcnt lgkmcnt(10)
	v_pk_fma_f32 v[48:49], v[72:73], v[32:33], v[48:49]
	ds_read_b128 v[172:175], v148 offset:7520
	v_pk_fma_f32 v[50:51], v[74:75], v[34:35], v[50:51]
	ds_read_b128 v[176:179], v148 offset:7536
	v_pk_fma_f32 v[48:49], v[76:77], v[36:37], v[48:49]
	ds_read2st64_b32 v[10:11], v149 offset0:30 offset1:31
	v_pk_fma_f32 v[50:51], v[78:79], v[38:39], v[50:51]
	v_pk_fma_f32 v[48:49], v[80:81], v[128:129], v[48:49]
	v_pk_fma_f32 v[50:51], v[82:83], v[130:131], v[50:51]
	s_waitcnt lgkmcnt(11)
	v_pk_fma_f32 v[48:49], v[84:85], v[132:133], v[48:49]
	ds_read_b128 v[180:183], v148 offset:7680
	v_pk_fma_f32 v[50:51], v[86:87], v[134:135], v[50:51]
	ds_read_b128 v[184:187], v148 offset:7696
	v_pk_fma_f32 v[48:49], v[88:89], v[136:137], v[48:49]
	v_pk_fma_f32 v[50:51], v[90:91], v[138:139], v[50:51]
	v_add_f32_e32 v1, v48, v49
	v_add_f32_e32 v2, v50, v51
	v_sub_f32_e64 v92, -v1, v2
	s_waitcnt lgkmcnt(10)
; #define LAS __attribute__((address_space(3)))
; __device__ __forceinline__ bf16_t f2bf(float f) { return (bf16_t)(pk2(f, 0.f) & 0xffffu); }
; template <int I, int C> __device__ __forceinline__ void s2_load(const LAS float* Ll, f32x4 (&lr)[16]) {
;     if constexpr (4 * C < I) { lr[C] = *(const LAS f32x4*)(Ll + I * 64 + 4 * C); s2_load<I, C + 1>(Ll, lr); }
; }
; template <int I, int C> __device__ __forceinline__ void s2_fma(const f32x4 (&lr)[16], const float (&Xc)[64], float& a0, float& a1, float& a2, float& a3) {
;     if constexpr (4 * C < I) {
;         a0 += lr[C].x * Xc[4 * C];
;         if constexpr (4 * C + 1 < I) a1 += lr[C].y * Xc[4 * C + 1];
;         if constexpr (4 * C + 2 < I) a2 += lr[C].z * Xc[4 * C + 2];
;         if constexpr (4 * C + 3 < I) a3 += lr[C].w * Xc[4 * C + 3];
;         s2_fma<I, C + 1>(lr, Xc, a0, a1, a2, a3);
;     }
; }
; template <int I> __device__ __forceinline__ void s2_row(const LAS float* Ll, float (&Xc)[64], int lane) {
;     if constexpr (I < 64) {
;         float a0 = Ll[I * 64 + lane], a1 = 0.f, a2 = 0.f, a3 = 0.f;
;         f32x4 lr[16];
;         s2_load<I, 0>(Ll, lr);
;         s2_fma<I, 0>(lr, Xc, a0, a1, a2, a3);
;         Xc[I] = -((a0 + a1) + (a2 + a3));
;         asm volatile("" ::: "memory");
;         s2_row<I + 1>(Ll, Xc, lane);
;     }
; }
; __device__ __forceinline__ void prep_task(LAS unsigned char* lds, const PrepP& P, int task, int tid, int lane, int wave) {
;     ...
;     if (wave == 0) {
;         float Xc[64];
;         s2_row<0>(Ll, Xc, lane);
; #pragma unroll
;         for (int i = 0; i < 64; ++i) Tl[i * TS + lane] = f2bf(Xc[i]);
;         asm volatile("s_waitcnt lgkmcnt(0)" ::: "memory");
;         Tl[lane * TS + lane] = (bf16_t)0x3F80u;
	v_fma_f32 v48, v64, v140, v9
	ds_read_b128 v[188:191], v148 offset:7712
	v_mul_f32_e32 v49, v65, v141
	ds_read_b128 v[200:203], v148 offset:7728
	v_pk_mul_f32 v[50:51], v[66:67], v[142:143]
	ds_read_b128 v[204:207], v148 offset:7744
	v_pk_fma_f32 v[48:49], v[68:69], v[144:145], v[48:49]
	v_pk_fma_f32 v[50:51], v[70:71], v[146:147], v[50:51]
	v_pk_fma_f32 v[48:49], v[72:73], v[156:157], v[48:49]
	v_pk_fma_f32 v[50:51], v[74:75], v[158:159], v[50:51]
	s_waitcnt lgkmcnt(11)
	v_pk_fma_f32 v[48:49], v[76:77], v[160:161], v[48:49]
	ds_read_b128 v[208:211], v148 offset:7760
	v_pk_fma_f32 v[50:51], v[78:79], v[162:163], v[50:51]
	ds_read_b128 v[212:215], v148 offset:7776
	v_pk_fma_f32 v[48:49], v[80:81], v[164:165], v[48:49]
	v_pk_fma_f32 v[50:51], v[82:83], v[166:167], v[50:51]
	s_waitcnt lgkmcnt(8)
	v_pk_fma_f32 v[48:49], v[84:85], v[168:169], v[48:49]
	ds_read_b128 v[216:219], v148 offset:7792
	v_pk_fma_f32 v[50:51], v[86:87], v[170:171], v[50:51]
	ds_read_b128 v[220:223], v148 offset:7936
	v_pk_fma_f32 v[48:49], v[88:89], v[172:173], v[48:49]
	ds_read_b128 v[224:227], v148 offset:7952
	v_pk_fma_f32 v[50:51], v[90:91], v[174:175], v[50:51]
	ds_read_b128 v[228:231], v148 offset:7968
	v_fma_f32 v48, v92, v176, v48
	ds_read_b128 v[232:235], v148 offset:7984
	v_add_f32_e32 v1, v48, v49
	v_add_f32_e32 v2, v50, v51
	v_sub_f32_e64 v93, -v1, v2
	v_cvt_pk_bf16_f32 v3, v92, v93
	ds_write_b16 v150, v3 offset:4032
	ds_write_b16_d16_hi v150, v3 offset:4176
	s_waitcnt lgkmcnt(12)
	v_fma_f32 v48, v64, v180, v10
	ds_read_b128 v[236:239], v148 offset:8000
	v_mul_f32_e32 v49, v65, v181
	v_pk_mul_f32 v[50:51], v[66:67], v[182:183]
	v_pk_fma_f32 v[48:49], v[68:69], v[184:185], v[48:49]
	v_pk_fma_f32 v[50:51], v[70:71], v[186:187], v[50:51]
	s_waitcnt lgkmcnt(10)
	v_pk_fma_f32 v[48:49], v[72:73], v[188:189], v[48:49]
	ds_read_b128 v[240:243], v148 offset:8016
	v_pk_fma_f32 v[50:51], v[74:75], v[190:191], v[50:51]
	ds_read_b128 v[244:247], v148 offset:8032
	v_pk_fma_f32 v[48:49], v[76:77], v[200:201], v[48:49]
	ds_read_b128 v[248:251], v148 offset:8048
	v_pk_fma_f32 v[50:51], v[78:79], v[202:203], v[50:51]
	v_pk_fma_f32 v[48:49], v[80:81], v[204:205], v[48:49]
	v_pk_fma_f32 v[50:51], v[82:83], v[206:207], v[50:51]
	s_waitcnt lgkmcnt(10)
	v_pk_fma_f32 v[48:49], v[84:85], v[208:209], v[48:49]
	ds_read2st64_b32 v[52:53], v149 offset0:32 offset1:33
	v_pk_fma_f32 v[50:51], v[86:87], v[210:211], v[50:51]
	ds_read_b128 v[12:15], v148 offset:8192
	v_pk_fma_f32 v[48:49], v[88:89], v[212:213], v[48:49]
	ds_read_b128 v[16:19], v148 offset:8208
	v_pk_fma_f32 v[50:51], v[90:91], v[214:215], v[50:51]
	v_pk_fma_f32 v[48:49], v[92:93], v[216:217], v[48:49]
	v_add_f32_e32 v1, v48, v49
	v_add_f32_e32 v2, v50, v51
	v_sub_f32_e64 v94, -v1, v2
	s_waitcnt lgkmcnt(10)
	v_fma_f32 v48, v64, v220, v11
	ds_read_b128 v[20:23], v148 offset:8224
	v_mul_f32_e32 v49, v65, v221
	ds_read_b128 v[24:27], v148 offset:8240
	v_pk_mul_f32 v[50:51], v[66:67], v[222:223]
	ds_read_b128 v[28:31], v148 offset:8256
	v_pk_fma_f32 v[48:49], v[68:69], v[224:225], v[48:49]
	v_pk_fma_f32 v[50:51], v[70:71], v[226:227], v[50:51]
	v_pk_fma_f32 v[48:49], v[72:73], v[228:229], v[48:49]
	v_pk_fma_f32 v[50:51], v[74:75], v[230:231], v[50:51]
	s_waitcnt lgkmcnt(12)
	v_pk_fma_f32 v[48:49], v[76:77], v[232:233], v[48:49]
	ds_read_b128 v[32:35], v148 offset:8272
	v_pk_fma_f32 v[50:51], v[78:79], v[234:235], v[50:51]
	s_waitcnt lgkmcnt(8)
	v_pk_fma_f32 v[48:49], v[80:81], v[236:237], v[48:49]
	ds_read_b128 v[36:39], v148 offset:8288
	v_pk_fma_f32 v[50:51], v[82:83], v[238:239], v[50:51]
	ds_read_b128 v[128:131], v148 offset:8304
	v_pk_fma_f32 v[48:49], v[84:85], v[240:241], v[48:49]
	ds_read_b128 v[132:135], v148 offset:8448
	v_pk_fma_f32 v[50:51], v[86:87], v[242:243], v[50:51]
	ds_read_b128 v[136:139], v148 offset:8464
	v_pk_fma_f32 v[48:49], v[88:89], v[244:245], v[48:49]
	ds_read_b128 v[140:143], v148 offset:8480
	v_pk_fma_f32 v[50:51], v[90:91], v[246:247], v[50:51]
	s_waitcnt lgkmcnt(12)
	v_pk_fma_f32 v[48:49], v[92:93], v[248:249], v[48:49]
	ds_read_b128 v[144:147], v148 offset:8496
	v_fma_f32 v50, v94, v250, v50
	v_add_f32_e32 v1, v48, v49
	v_add_f32_e32 v2, v50, v51
	v_sub_f32_e64 v95, -v1, v2
	v_cvt_pk_bf16_f32 v3, v94, v95
	ds_write_b16 v150, v3 offset:4320
	ds_write_b16_d16_hi v150, v3 offset:4464
	s_waitcnt lgkmcnt(12)
	v_fma_f32 v48, v64, v12, v52
	ds_read_b128 v[156:159], v148 offset:8512
	v_mul_f32_e32 v49, v65, v13
	v_pk_mul_f32 v[50:51], v[66:67], v[14:15]
	v_pk_fma_f32 v[48:49], v[68:69], v[16:17], v[48:49]
	v_pk_fma_f32 v[50:51], v[70:71], v[18:19], v[50:51]
	s_waitcnt lgkmcnt(10)
	v_pk_fma_f32 v[48:49], v[72:73], v[20:21], v[48:49]
	ds_read_b128 v[160:163], v148 offset:8528
	v_pk_fma_f32 v[50:51], v[74:75], v[22:23], v[50:51]
	ds_read_b128 v[164:167], v148 offset:8544
	v_pk_fma_f32 v[48:49], v[76:77], v[24:25], v[48:49]
	ds_read_b128 v[168:171], v148 offset:8560
	v_pk_fma_f32 v[50:51], v[78:79], v[26:27], v[50:51]
	v_pk_fma_f32 v[48:49], v[80:81], v[28:29], v[48:49]
	v_pk_fma_f32 v[50:51], v[82:83], v[30:31], v[50:51]
	s_waitcnt lgkmcnt(10)
	v_pk_fma_f32 v[48:49], v[84:85], v[32:33], v[48:49]
	ds_read_b128 v[172:175], v148 offset:8576
	v_pk_fma_f32 v[50:51], v[86:87], v[34:35], v[50:51]
	ds_read2st64_b32 v[252:253], v149 offset0:34 offset1:35
	v_pk_fma_f32 v[48:49], v[88:89], v[36:37], v[48:49]
	ds_read_b128 v[176:179], v148 offset:8704
	v_pk_fma_f32 v[50:51], v[90:91], v[38:39], v[50:51]
	v_pk_fma_f32 v[48:49], v[92:93], v[128:129], v[48:49]
	v_pk_fma_f32 v[50:51], v[94:95], v[130:131], v[50:51]
	v_add_f32_e32 v1, v48, v49
	v_add_f32_e32 v2, v50, v51
	v_sub_f32_e64 v96, -v1, v2
	s_waitcnt lgkmcnt(10)
; #define LAS __attribute__((address_space(3)))
; __device__ __forceinline__ bf16_t f2bf(float f) { return (bf16_t)(pk2(f, 0.f) & 0xffffu); }
; template <int I, int C> __device__ __forceinline__ void s2_load(const LAS float* Ll, f32x4 (&lr)[16]) {
;     if constexpr (4 * C < I) { lr[C] = *(const LAS f32x4*)(Ll + I * 64 + 4 * C); s2_load<I, C + 1>(Ll, lr); }
; }
; template <int I, int C> __device__ __forceinline__ void s2_fma(const f32x4 (&lr)[16], const float (&Xc)[64], float& a0, float& a1, float& a2, float& a3) {
;     if constexpr (4 * C < I) {
;         a0 += lr[C].x * Xc[4 * C];
;         if constexpr (4 * C + 1 < I) a1 += lr[C].y * Xc[4 * C + 1];
;         if constexpr (4 * C + 2 < I) a2 += lr[C].z * Xc[4 * C + 2];
;         if constexpr (4 * C + 3 < I) a3 += lr[C].w * Xc[4 * C + 3];
;         s2_fma<I, C + 1>(lr, Xc, a0, a1, a2, a3);
;     }
; }
; template <int I> __device__ __forceinline__ void s2_row(const LAS float* Ll, float (&Xc)[64], int lane) {
;     if constexpr (I < 64) {
;         float a0 = Ll[I * 64 + lane], a1 = 0.f, a2 = 0.f, a3 = 0.f;
;         f32x4 lr[16];
;         s2_load<I, 0>(Ll, lr);
;         s2_fma<I, 0>(lr, Xc, a0, a1, a2, a3);
;         Xc[I] = -((a0 + a1) + (a2 + a3));
;         asm volatile("" ::: "memory");
;         s2_row<I + 1>(Ll, Xc, lane);
;     }
; }
; __device__ __forceinline__ void prep_task(LAS unsigned char* lds, const PrepP& P, int task, int tid, int lane, int wave) {
;     ...
;     if (wave == 0) {
;         float Xc[64];
;         s2_row<0>(Ll, Xc, lane);
; #pragma unroll
;         for (int i = 0; i < 64; ++i) Tl[i * TS + lane] = f2bf(Xc[i]);
;         asm volatile("s_waitcnt lgkmcnt(0)" ::: "memory");
;         Tl[lane * TS + lane] = (bf16_t)0x3F80u;
	v_fma_f32 v48, v64, v132, v53
	ds_read_b128 v[180:183], v148 offset:8720
	v_mul_f32_e32 v49, v65, v133
	ds_read_b128 v[184:187], v148 offset:8736
	v_pk_mul_f32 v[50:51], v[66:67], v[134:135]
	ds_read_b128 v[188:191], v148 offset:8752
	v_pk_fma_f32 v[48:49], v[68:69], v[136:137], v[48:49]
	v_pk_fma_f32 v[50:51], v[70:71], v[138:139], v[50:51]
	v_pk_fma_f32 v[48:49], v[72:73], v[140:141], v[48:49]
	v_pk_fma_f32 v[50:51], v[74:75], v[142:143], v[50:51]
	s_waitcnt lgkmcnt(12)
	v_pk_fma_f32 v[48:49], v[76:77], v[144:145], v[48:49]
	ds_read_b128 v[200:203], v148 offset:8768
	v_pk_fma_f32 v[50:51], v[78:79], v[146:147], v[50:51]
	s_waitcnt lgkmcnt(8)
	v_pk_fma_f32 v[48:49], v[80:81], v[156:157], v[48:49]
	ds_read_b128 v[204:207], v148 offset:8784
	v_pk_fma_f32 v[50:51], v[82:83], v[158:159], v[50:51]
	ds_read_b128 v[208:211], v148 offset:8800
	v_pk_fma_f32 v[48:49], v[84:85], v[160:161], v[48:49]
	ds_read_b128 v[212:215], v148 offset:8816
	v_pk_fma_f32 v[50:51], v[86:87], v[162:163], v[50:51]
	ds_read_b128 v[216:219], v148 offset:8832
	v_pk_fma_f32 v[48:49], v[88:89], v[164:165], v[48:49]
	ds_read_b128 v[220:223], v148 offset:8960
	v_pk_fma_f32 v[50:51], v[90:91], v[166:167], v[50:51]
	s_waitcnt lgkmcnt(11)
	v_pk_fma_f32 v[48:49], v[92:93], v[168:169], v[48:49]
	ds_read_b128 v[224:227], v148 offset:8976
	v_pk_fma_f32 v[50:51], v[94:95], v[170:171], v[50:51]
	ds_read_b128 v[228:231], v148 offset:8992
	v_fma_f32 v48, v96, v172, v48
	v_add_f32_e32 v1, v48, v49
	v_add_f32_e32 v2, v50, v51
	v_sub_f32_e64 v97, -v1, v2
	v_cvt_pk_bf16_f32 v3, v96, v97
	ds_write_b16 v150, v3 offset:4608
	ds_write_b16_d16_hi v150, v3 offset:4752
	s_waitcnt lgkmcnt(12)
	v_fma_f32 v48, v64, v176, v252
	ds_read_b128 v[232:235], v148 offset:9008
	v_mul_f32_e32 v49, v65, v177
	v_pk_mul_f32 v[50:51], v[66:67], v[178:179]
	v_pk_fma_f32 v[48:49], v[68:69], v[180:181], v[48:49]
	v_pk_fma_f32 v[50:51], v[70:71], v[182:183], v[50:51]
	s_waitcnt lgkmcnt(10)
	v_pk_fma_f32 v[48:49], v[72:73], v[184:185], v[48:49]
	ds_read_b128 v[236:239], v148 offset:9024
	v_pk_fma_f32 v[50:51], v[74:75], v[186:187], v[50:51]
	ds_read_b128 v[240:243], v148 offset:9040
	v_pk_fma_f32 v[48:49], v[76:77], v[188:189], v[48:49]
	ds_read_b128 v[244:247], v148 offset:9056
	v_pk_fma_f32 v[50:51], v[78:79], v[190:191], v[50:51]
	v_pk_fma_f32 v[48:49], v[80:81], v[200:201], v[48:49]
	v_pk_fma_f32 v[50:51], v[82:83], v[202:203], v[50:51]
	s_waitcnt lgkmcnt(10)
	v_pk_fma_f32 v[48:49], v[84:85], v[204:205], v[48:49]
	ds_read_b128 v[248:251], v148 offset:9072
	v_pk_fma_f32 v[50:51], v[86:87], v[206:207], v[50:51]
	ds_read_b128 v[12:15], v148 offset:9088
	v_pk_fma_f32 v[48:49], v[88:89], v[208:209], v[48:49]
	ds_read2st64_b32 v[4:5], v149 offset0:36 offset1:37
	v_pk_fma_f32 v[50:51], v[90:91], v[210:211], v[50:51]
	v_pk_fma_f32 v[48:49], v[92:93], v[212:213], v[48:49]
	v_pk_fma_f32 v[50:51], v[94:95], v[214:215], v[50:51]
	s_waitcnt lgkmcnt(12)
	v_pk_fma_f32 v[48:49], v[96:97], v[216:217], v[48:49]
	ds_read_b128 v[16:19], v148 offset:9216
	v_add_f32_e32 v1, v48, v49
	v_add_f32_e32 v2, v50, v51
	v_sub_f32_e64 v98, -v1, v2
	s_waitcnt lgkmcnt(10)
	v_fma_f32 v48, v64, v220, v253
	ds_read_b128 v[20:23], v148 offset:9232
	v_mul_f32_e32 v49, v65, v221
	ds_read_b128 v[24:27], v148 offset:9248
	v_pk_mul_f32 v[50:51], v[66:67], v[222:223]
	ds_read_b128 v[28:31], v148 offset:9264
	v_pk_fma_f32 v[48:49], v[68:69], v[224:225], v[48:49]
	v_pk_fma_f32 v[50:51], v[70:71], v[226:227], v[50:51]
	v_pk_fma_f32 v[48:49], v[72:73], v[228:229], v[48:49]
	v_pk_fma_f32 v[50:51], v[74:75], v[230:231], v[50:51]
	s_waitcnt lgkmcnt(8)
	v_pk_fma_f32 v[48:49], v[76:77], v[232:233], v[48:49]
	ds_read_b128 v[32:35], v148 offset:9280
	v_pk_fma_f32 v[50:51], v[78:79], v[234:235], v[50:51]
	ds_read_b128 v[36:39], v148 offset:9296
	v_pk_fma_f32 v[48:49], v[80:81], v[236:237], v[48:49]
	ds_read_b128 v[128:131], v148 offset:9312
	v_pk_fma_f32 v[50:51], v[82:83], v[238:239], v[50:51]
	ds_read_b128 v[132:135], v148 offset:9328
	v_pk_fma_f32 v[48:49], v[84:85], v[240:241], v[48:49]
	ds_read_b128 v[136:139], v148 offset:9344
	v_pk_fma_f32 v[50:51], v[86:87], v[242:243], v[50:51]
	s_waitcnt lgkmcnt(10)
	v_pk_fma_f32 v[48:49], v[88:89], v[244:245], v[48:49]
	ds_read_b128 v[140:143], v148 offset:9472
	v_pk_fma_f32 v[50:51], v[90:91], v[246:247], v[50:51]
	ds_read_b128 v[144:147], v148 offset:9488
	v_pk_fma_f32 v[48:49], v[92:93], v[248:249], v[48:49]
	ds_read_b128 v[156:159], v148 offset:9504
	v_pk_fma_f32 v[50:51], v[94:95], v[250:251], v[50:51]
	v_pk_fma_f32 v[48:49], v[96:97], v[12:13], v[48:49]
	v_fma_f32 v50, v98, v14, v50
	v_add_f32_e32 v1, v48, v49
	v_add_f32_e32 v2, v50, v51
	v_sub_f32_e64 v99, -v1, v2
	v_cvt_pk_bf16_f32 v3, v98, v99
	ds_write_b16 v150, v3 offset:4896
	ds_write_b16_d16_hi v150, v3 offset:5040
	s_waitcnt lgkmcnt(12)
	v_fma_f32 v48, v64, v16, v4
	ds_read_b128 v[160:163], v148 offset:9520
	v_mul_f32_e32 v49, v65, v17
	v_pk_mul_f32 v[50:51], v[66:67], v[18:19]
	v_pk_fma_f32 v[48:49], v[68:69], v[20:21], v[48:49]
	v_pk_fma_f32 v[50:51], v[70:71], v[22:23], v[50:51]
	s_waitcnt lgkmcnt(10)
	v_pk_fma_f32 v[48:49], v[72:73], v[24:25], v[48:49]
	ds_read_b128 v[164:167], v148 offset:9536
	v_pk_fma_f32 v[50:51], v[74:75], v[26:27], v[50:51]
	ds_read_b128 v[168:171], v148 offset:9552
	v_pk_fma_f32 v[48:49], v[76:77], v[28:29], v[48:49]
	ds_read_b128 v[172:175], v148 offset:9568
	v_pk_fma_f32 v[50:51], v[78:79], v[30:31], v[50:51]
	v_pk_fma_f32 v[48:49], v[80:81], v[32:33], v[48:49]
	v_pk_fma_f32 v[50:51], v[82:83], v[34:35], v[50:51]
	s_waitcnt lgkmcnt(10)
; #define LAS __attribute__((address_space(3)))
; __device__ __forceinline__ bf16_t f2bf(float f) { return (bf16_t)(pk2(f, 0.f) & 0xffffu); }
; template <int I, int C> __device__ __forceinline__ void s2_load(const LAS float* Ll, f32x4 (&lr)[16]) {
;     if constexpr (4 * C < I) { lr[C] = *(const LAS f32x4*)(Ll + I * 64 + 4 * C); s2_load<I, C + 1>(Ll, lr); }
; }
; template <int I, int C> __device__ __forceinline__ void s2_fma(const f32x4 (&lr)[16], const float (&Xc)[64], float& a0, float& a1, float& a2, float& a3) {
;     if constexpr (4 * C < I) {
;         a0 += lr[C].x * Xc[4 * C];
;         if constexpr (4 * C + 1 < I) a1 += lr[C].y * Xc[4 * C + 1];
;         if constexpr (4 * C + 2 < I) a2 += lr[C].z * Xc[4 * C + 2];
;         if constexpr (4 * C + 3 < I) a3 += lr[C].w * Xc[4 * C + 3];
;         s2_fma<I, C + 1>(lr, Xc, a0, a1, a2, a3);
;     }
; }
; template <int I> __device__ __forceinline__ void s2_row(const LAS float* Ll, float (&Xc)[64], int lane) {
;     if constexpr (I < 64) {
;         float a0 = Ll[I * 64 + lane], a1 = 0.f, a2 = 0.f, a3 = 0.f;
;         f32x4 lr[16];
;         s2_load<I, 0>(Ll, lr);
;         s2_fma<I, 0>(lr, Xc, a0, a1, a2, a3);
;         Xc[I] = -((a0 + a1) + (a2 + a3));
;         asm volatile("" ::: "memory");
;         s2_row<I + 1>(Ll, Xc, lane);
;     }
; }
; __device__ __forceinline__ void prep_task(LAS unsigned char* lds, const PrepP& P, int task, int tid, int lane, int wave) {
;     ...
;     if (wave == 0) {
;         float Xc[64];
;         s2_row<0>(Ll, Xc, lane);
; #pragma unroll
;         for (int i = 0; i < 64; ++i) Tl[i * TS + lane] = f2bf(Xc[i]);
;         asm volatile("s_waitcnt lgkmcnt(0)" ::: "memory");
;         Tl[lane * TS + lane] = (bf16_t)0x3F80u;
	v_pk_fma_f32 v[48:49], v[84:85], v[36:37], v[48:49]
	ds_read_b128 v[176:179], v148 offset:9584
	v_pk_fma_f32 v[50:51], v[86:87], v[38:39], v[50:51]
	ds_read_b128 v[180:183], v148 offset:9600
	v_pk_fma_f32 v[48:49], v[88:89], v[128:129], v[48:49]
	ds_read_b128 v[184:187], v148 offset:9616
	v_pk_fma_f32 v[50:51], v[90:91], v[130:131], v[50:51]
	v_pk_fma_f32 v[48:49], v[92:93], v[132:133], v[48:49]
	v_pk_fma_f32 v[50:51], v[94:95], v[134:135], v[50:51]
	s_waitcnt lgkmcnt(12)
	v_pk_fma_f32 v[48:49], v[96:97], v[136:137], v[48:49]
	ds_read2st64_b32 v[6:7], v149 offset0:38 offset1:39
	v_pk_fma_f32 v[50:51], v[98:99], v[138:139], v[50:51]
	v_add_f32_e32 v1, v48, v49
	v_add_f32_e32 v2, v50, v51
	v_sub_f32_e64 v100, -v1, v2
	s_waitcnt lgkmcnt(10)
	v_fma_f32 v48, v64, v140, v5
	ds_read_b128 v[188:191], v148 offset:9728
	v_mul_f32_e32 v49, v65, v141
	ds_read_b128 v[200:203], v148 offset:9744
	v_pk_mul_f32 v[50:51], v[66:67], v[142:143]
	ds_read_b128 v[204:207], v148 offset:9760
	v_pk_fma_f32 v[48:49], v[68:69], v[144:145], v[48:49]
	v_pk_fma_f32 v[50:51], v[70:71], v[146:147], v[50:51]
	v_pk_fma_f32 v[48:49], v[72:73], v[156:157], v[48:49]
	v_pk_fma_f32 v[50:51], v[74:75], v[158:159], v[50:51]
	s_waitcnt lgkmcnt(8)
	v_pk_fma_f32 v[48:49], v[76:77], v[160:161], v[48:49]
	ds_read_b128 v[208:211], v148 offset:9776
	v_pk_fma_f32 v[50:51], v[78:79], v[162:163], v[50:51]
	ds_read_b128 v[212:215], v148 offset:9792
	v_pk_fma_f32 v[48:49], v[80:81], v[164:165], v[48:49]
	ds_read_b128 v[216:219], v148 offset:9808
	v_pk_fma_f32 v[50:51], v[82:83], v[166:167], v[50:51]
	ds_read_b128 v[220:223], v148 offset:9824
	v_pk_fma_f32 v[48:49], v[84:85], v[168:169], v[48:49]
	ds_read_b128 v[224:227], v148 offset:9840
	v_pk_fma_f32 v[50:51], v[86:87], v[170:171], v[50:51]
	s_waitcnt lgkmcnt(10)
	v_pk_fma_f32 v[48:49], v[88:89], v[172:173], v[48:49]
	ds_read_b128 v[228:231], v148 offset:9856
	v_pk_fma_f32 v[50:51], v[90:91], v[174:175], v[50:51]
	ds_read_b128 v[232:235], v148 offset:9872
	v_pk_fma_f32 v[48:49], v[92:93], v[176:177], v[48:49]
	ds_read_b128 v[236:239], v148 offset:9984
	v_pk_fma_f32 v[50:51], v[94:95], v[178:179], v[50:51]
	v_pk_fma_f32 v[48:49], v[96:97], v[180:181], v[48:49]
	v_pk_fma_f32 v[50:51], v[98:99], v[182:183], v[50:51]
	s_waitcnt lgkmcnt(12)
	v_fma_f32 v48, v100, v184, v48
	ds_read_b128 v[240:243], v148 offset:10000
	v_add_f32_e32 v1, v48, v49
	v_add_f32_e32 v2, v50, v51
	v_sub_f32_e64 v101, -v1, v2
	v_cvt_pk_bf16_f32 v3, v100, v101
	ds_write_b16 v150, v3 offset:5184
	ds_write_b16_d16_hi v150, v3 offset:5328
	s_waitcnt lgkmcnt(12)
	v_fma_f32 v48, v64, v188, v6
	ds_read_b128 v[244:247], v148 offset:10016
	v_mul_f32_e32 v49, v65, v189
	v_pk_mul_f32 v[50:51], v[66:67], v[190:191]
	v_pk_fma_f32 v[48:49], v[68:69], v[200:201], v[48:49]
	v_pk_fma_f32 v[50:51], v[70:71], v[202:203], v[50:51]
	s_waitcnt lgkmcnt(10)
	v_pk_fma_f32 v[48:49], v[72:73], v[204:205], v[48:49]
	ds_read_b128 v[248:251], v148 offset:10032
	v_pk_fma_f32 v[50:51], v[74:75], v[206:207], v[50:51]
	ds_read_b128 v[12:15], v148 offset:10048
	v_pk_fma_f32 v[48:49], v[76:77], v[208:209], v[48:49]
	ds_read_b128 v[16:19], v148 offset:10064
	v_pk_fma_f32 v[50:51], v[78:79], v[210:211], v[50:51]
	v_pk_fma_f32 v[48:49], v[80:81], v[212:213], v[48:49]
	v_pk_fma_f32 v[50:51], v[82:83], v[214:215], v[50:51]
	s_waitcnt lgkmcnt(10)
	v_pk_fma_f32 v[48:49], v[84:85], v[216:217], v[48:49]
	ds_read_b128 v[20:23], v148 offset:10080
	v_pk_fma_f32 v[50:51], v[86:87], v[218:219], v[50:51]
	ds_read_b128 v[24:27], v148 offset:10096
	v_pk_fma_f32 v[48:49], v[88:89], v[220:221], v[48:49]
	ds_read_b128 v[28:31], v148 offset:10112
	v_pk_fma_f32 v[50:51], v[90:91], v[222:223], v[50:51]
	v_pk_fma_f32 v[48:49], v[92:93], v[224:225], v[48:49]
	v_pk_fma_f32 v[50:51], v[94:95], v[226:227], v[50:51]
	s_waitcnt lgkmcnt(11)
	v_pk_fma_f32 v[48:49], v[96:97], v[228:229], v[48:49]
	ds_read_b128 v[32:35], v148 offset:10128
	v_pk_fma_f32 v[50:51], v[98:99], v[230:231], v[50:51]
	ds_read2st64_b32 v[8:9], v149 offset0:40 offset1:41
	v_pk_fma_f32 v[48:49], v[100:101], v[232:233], v[48:49]
	v_add_f32_e32 v1, v48, v49
	v_add_f32_e32 v2, v50, v51
	v_sub_f32_e64 v102, -v1, v2
	s_waitcnt lgkmcnt(11)
	v_fma_f32 v48, v64, v236, v7
	ds_read_b128 v[36:39], v148 offset:10240
	v_mul_f32_e32 v49, v65, v237
	ds_read_b128 v[128:131], v148 offset:10256
	v_pk_mul_f32 v[50:51], v[66:67], v[238:239]
	v_pk_fma_f32 v[48:49], v[68:69], v[240:241], v[48:49]
	v_pk_fma_f32 v[50:51], v[70:71], v[242:243], v[50:51]
	s_waitcnt lgkmcnt(8)
	v_pk_fma_f32 v[48:49], v[72:73], v[244:245], v[48:49]
	ds_read_b128 v[132:135], v148 offset:10272
	v_pk_fma_f32 v[50:51], v[74:75], v[246:247], v[50:51]
	ds_read_b128 v[136:139], v148 offset:10288
	v_pk_fma_f32 v[48:49], v[76:77], v[248:249], v[48:49]
	ds_read_b128 v[140:143], v148 offset:10304
	v_pk_fma_f32 v[50:51], v[78:79], v[250:251], v[50:51]
	ds_read_b128 v[144:147], v148 offset:10320
	v_pk_fma_f32 v[48:49], v[80:81], v[12:13], v[48:49]
	ds_read_b128 v[156:159], v148 offset:10336
	v_pk_fma_f32 v[50:51], v[82:83], v[14:15], v[50:51]
	s_waitcnt lgkmcnt(10)
	v_pk_fma_f32 v[48:49], v[84:85], v[16:17], v[48:49]
	ds_read_b128 v[160:163], v148 offset:10352
	v_pk_fma_f32 v[50:51], v[86:87], v[18:19], v[50:51]
	ds_read_b128 v[164:167], v148 offset:10368
	v_pk_fma_f32 v[48:49], v[88:89], v[20:21], v[48:49]
	ds_read_b128 v[168:171], v148 offset:10384
	v_pk_fma_f32 v[50:51], v[90:91], v[22:23], v[50:51]
	v_pk_fma_f32 v[48:49], v[92:93], v[24:25], v[48:49]
	v_pk_fma_f32 v[50:51], v[94:95], v[26:27], v[50:51]
	s_waitcnt lgkmcnt(11)
; #define LAS __attribute__((address_space(3)))
; __device__ __forceinline__ bf16_t f2bf(float f) { return (bf16_t)(pk2(f, 0.f) & 0xffffu); }
; template <int I, int C> __device__ __forceinline__ void s2_load(const LAS float* Ll, f32x4 (&lr)[16]) {
;     if constexpr (4 * C < I) { lr[C] = *(const LAS f32x4*)(Ll + I * 64 + 4 * C); s2_load<I, C + 1>(Ll, lr); }
; }
; template <int I, int C> __device__ __forceinline__ void s2_fma(const f32x4 (&lr)[16], const float (&Xc)[64], float& a0, float& a1, float& a2, float& a3) {
;     if constexpr (4 * C < I) {
;         a0 += lr[C].x * Xc[4 * C];
;         if constexpr (4 * C + 1 < I) a1 += lr[C].y * Xc[4 * C + 1];
;         if constexpr (4 * C + 2 < I) a2 += lr[C].z * Xc[4 * C + 2];
;         if constexpr (4 * C + 3 < I) a3 += lr[C].w * Xc[4 * C + 3];
;         s2_fma<I, C + 1>(lr, Xc, a0, a1, a2, a3);
;     }
; }
; template <int I> __device__ __forceinline__ void s2_row(const LAS float* Ll, float (&Xc)[64], int lane) {
;     if constexpr (I < 64) {
;         float a0 = Ll[I * 64 + lane], a1 = 0.f, a2 = 0.f, a3 = 0.f;
;         f32x4 lr[16];
;         s2_load<I, 0>(Ll, lr);
;         s2_fma<I, 0>(lr, Xc, a0, a1, a2, a3);
;         Xc[I] = -((a0 + a1) + (a2 + a3));
;         asm volatile("" ::: "memory");
;         s2_row<I + 1>(Ll, Xc, lane);
;     }
; }
; __device__ __forceinline__ void prep_task(LAS unsigned char* lds, const PrepP& P, int task, int tid, int lane, int wave) {
;     ...
;     if (wave == 0) {
;         float Xc[64];
;         s2_row<0>(Ll, Xc, lane);
; #pragma unroll
;         for (int i = 0; i < 64; ++i) Tl[i * TS + lane] = f2bf(Xc[i]);
;         asm volatile("s_waitcnt lgkmcnt(0)" ::: "memory");
;         Tl[lane * TS + lane] = (bf16_t)0x3F80u;
	v_pk_fma_f32 v[48:49], v[96:97], v[28:29], v[48:49]
	ds_read_b128 v[172:175], v148 offset:10496
	v_pk_fma_f32 v[50:51], v[98:99], v[30:31], v[50:51]
	ds_read_b128 v[176:179], v148 offset:10512
	v_pk_fma_f32 v[48:49], v[100:101], v[32:33], v[48:49]
	v_fma_f32 v50, v102, v34, v50
	v_add_f32_e32 v1, v48, v49
	v_add_f32_e32 v2, v50, v51
	v_sub_f32_e64 v103, -v1, v2
	v_cvt_pk_bf16_f32 v3, v102, v103
	ds_write_b16 v150, v3 offset:5472
	ds_write_b16_d16_hi v150, v3 offset:5616
	s_waitcnt lgkmcnt(12)
	v_fma_f32 v48, v64, v36, v8
	ds_read_b128 v[180:183], v148 offset:10528
	v_mul_f32_e32 v49, v65, v37
	v_pk_mul_f32 v[50:51], v[66:67], v[38:39]
	v_pk_fma_f32 v[48:49], v[68:69], v[128:129], v[48:49]
	v_pk_fma_f32 v[50:51], v[70:71], v[130:131], v[50:51]
	s_waitcnt lgkmcnt(10)
	v_pk_fma_f32 v[48:49], v[72:73], v[132:133], v[48:49]
	ds_read_b128 v[184:187], v148 offset:10544
	v_pk_fma_f32 v[50:51], v[74:75], v[134:135], v[50:51]
	ds_read_b128 v[188:191], v148 offset:10560
	v_pk_fma_f32 v[48:49], v[76:77], v[136:137], v[48:49]
	ds_read_b128 v[200:203], v148 offset:10576
	v_pk_fma_f32 v[50:51], v[78:79], v[138:139], v[50:51]
	v_pk_fma_f32 v[48:49], v[80:81], v[140:141], v[48:49]
	v_pk_fma_f32 v[50:51], v[82:83], v[142:143], v[50:51]
	s_waitcnt lgkmcnt(10)
	v_pk_fma_f32 v[48:49], v[84:85], v[144:145], v[48:49]
	ds_read_b128 v[204:207], v148 offset:10592
	v_pk_fma_f32 v[50:51], v[86:87], v[146:147], v[50:51]
	ds_read_b128 v[208:211], v148 offset:10608
	v_pk_fma_f32 v[48:49], v[88:89], v[156:157], v[48:49]
	ds_read_b128 v[212:215], v148 offset:10624
	v_pk_fma_f32 v[50:51], v[90:91], v[158:159], v[50:51]
	v_pk_fma_f32 v[48:49], v[92:93], v[160:161], v[48:49]
	v_pk_fma_f32 v[50:51], v[94:95], v[162:163], v[50:51]
	s_waitcnt lgkmcnt(11)
	v_pk_fma_f32 v[48:49], v[96:97], v[164:165], v[48:49]
	ds_read_b128 v[216:219], v148 offset:10640
	v_pk_fma_f32 v[50:51], v[98:99], v[166:167], v[50:51]
	ds_read_b128 v[220:223], v148 offset:10656
	v_pk_fma_f32 v[48:49], v[100:101], v[168:169], v[48:49]
	v_pk_fma_f32 v[50:51], v[102:103], v[170:171], v[50:51]
	v_add_f32_e32 v1, v48, v49
	v_add_f32_e32 v2, v50, v51
	v_sub_f32_e64 v104, -v1, v2
	s_waitcnt lgkmcnt(11)
	v_fma_f32 v48, v64, v172, v9
	ds_read2st64_b32 v[10:11], v149 offset0:42 offset1:43
	v_mul_f32_e32 v49, v65, v173
	ds_read_b128 v[224:227], v148 offset:10752
	v_pk_mul_f32 v[50:51], v[66:67], v[174:175]
	v_pk_fma_f32 v[48:49], v[68:69], v[176:177], v[48:49]
	v_pk_fma_f32 v[50:51], v[70:71], v[178:179], v[50:51]
	s_waitcnt lgkmcnt(8)
	v_pk_fma_f32 v[48:49], v[72:73], v[180:181], v[48:49]
	ds_read_b128 v[228:231], v148 offset:10768
	v_pk_fma_f32 v[50:51], v[74:75], v[182:183], v[50:51]
	ds_read_b128 v[232:235], v148 offset:10784
	v_pk_fma_f32 v[48:49], v[76:77], v[184:185], v[48:49]
	ds_read_b128 v[236:239], v148 offset:10800
	v_pk_fma_f32 v[50:51], v[78:79], v[186:187], v[50:51]
	ds_read_b128 v[240:243], v148 offset:10816
	v_pk_fma_f32 v[48:49], v[80:81], v[188:189], v[48:49]
	ds_read_b128 v[244:247], v148 offset:10832
	v_pk_fma_f32 v[50:51], v[82:83], v[190:191], v[50:51]
	s_waitcnt lgkmcnt(10)
	v_pk_fma_f32 v[48:49], v[84:85], v[200:201], v[48:49]
	ds_read_b128 v[248:251], v148 offset:10848
	v_pk_fma_f32 v[50:51], v[86:87], v[202:203], v[50:51]
	ds_read_b128 v[12:15], v148 offset:10864
	v_pk_fma_f32 v[48:49], v[88:89], v[204:205], v[48:49]
	ds_read_b128 v[16:19], v148 offset:10880
	v_pk_fma_f32 v[50:51], v[90:91], v[206:207], v[50:51]
	v_pk_fma_f32 v[48:49], v[92:93], v[208:209], v[48:49]
	v_pk_fma_f32 v[50:51], v[94:95], v[210:211], v[50:51]
	s_waitcnt lgkmcnt(10)
	v_pk_fma_f32 v[48:49], v[96:97], v[212:213], v[48:49]
	ds_read_b128 v[20:23], v148 offset:10896
	v_pk_fma_f32 v[50:51], v[98:99], v[214:215], v[50:51]
	ds_read_b128 v[24:27], v148 offset:10912
	v_pk_fma_f32 v[48:49], v[100:101], v[216:217], v[48:49]
	ds_read_b128 v[28:31], v148 offset:11008
	v_pk_fma_f32 v[50:51], v[102:103], v[218:219], v[50:51]
	v_fma_f32 v48, v104, v220, v48
	v_add_f32_e32 v1, v48, v49
	v_add_f32_e32 v2, v50, v51
	v_sub_f32_e64 v105, -v1, v2
	v_cvt_pk_bf16_f32 v3, v104, v105
	ds_write_b16 v150, v3 offset:5760
	ds_write_b16_d16_hi v150, v3 offset:5904
	s_waitcnt lgkmcnt(12)
	v_fma_f32 v48, v64, v224, v10
	ds_read_b128 v[32:35], v148 offset:11024
	v_mul_f32_e32 v49, v65, v225
	v_pk_mul_f32 v[50:51], v[66:67], v[226:227]
	v_pk_fma_f32 v[48:49], v[68:69], v[228:229], v[48:49]
	v_pk_fma_f32 v[50:51], v[70:71], v[230:231], v[50:51]
	s_waitcnt lgkmcnt(10)
	v_pk_fma_f32 v[48:49], v[72:73], v[232:233], v[48:49]
	ds_read_b128 v[36:39], v148 offset:11040
	v_pk_fma_f32 v[50:51], v[74:75], v[234:235], v[50:51]
	ds_read_b128 v[128:131], v148 offset:11056
	v_pk_fma_f32 v[48:49], v[76:77], v[236:237], v[48:49]
	ds_read_b128 v[132:135], v148 offset:11072
	v_pk_fma_f32 v[50:51], v[78:79], v[238:239], v[50:51]
	v_pk_fma_f32 v[48:49], v[80:81], v[240:241], v[48:49]
	v_pk_fma_f32 v[50:51], v[82:83], v[242:243], v[50:51]
	s_waitcnt lgkmcnt(10)
	v_pk_fma_f32 v[48:49], v[84:85], v[244:245], v[48:49]
	ds_read_b128 v[136:139], v148 offset:11088
	v_pk_fma_f32 v[50:51], v[86:87], v[246:247], v[50:51]
	ds_read_b128 v[140:143], v148 offset:11104
	v_pk_fma_f32 v[48:49], v[88:89], v[248:249], v[48:49]
	ds_read_b128 v[144:147], v148 offset:11120
	v_pk_fma_f32 v[50:51], v[90:91], v[250:251], v[50:51]
	v_pk_fma_f32 v[48:49], v[92:93], v[12:13], v[48:49]
	v_pk_fma_f32 v[50:51], v[94:95], v[14:15], v[50:51]
	s_waitcnt lgkmcnt(10)
; #define LAS __attribute__((address_space(3)))
; __device__ __forceinline__ bf16_t f2bf(float f) { return (bf16_t)(pk2(f, 0.f) & 0xffffu); }
; template <int I, int C> __device__ __forceinline__ void s2_load(const LAS float* Ll, f32x4 (&lr)[16]) {
;     if constexpr (4 * C < I) { lr[C] = *(const LAS f32x4*)(Ll + I * 64 + 4 * C); s2_load<I, C + 1>(Ll, lr); }
; }
; template <int I, int C> __device__ __forceinline__ void s2_fma(const f32x4 (&lr)[16], const float (&Xc)[64], float& a0, float& a1, float& a2, float& a3) {
;     if constexpr (4 * C < I) {
;         a0 += lr[C].x * Xc[4 * C];
;         if constexpr (4 * C + 1 < I) a1 += lr[C].y * Xc[4 * C + 1];
;         if constexpr (4 * C + 2 < I) a2 += lr[C].z * Xc[4 * C + 2];
;         if constexpr (4 * C + 3 < I) a3 += lr[C].w * Xc[4 * C + 3];
;         s2_fma<I, C + 1>(lr, Xc, a0, a1, a2, a3);
;     }
; }
; template <int I> __device__ __forceinline__ void s2_row(const LAS float* Ll, float (&Xc)[64], int lane) {
;     if constexpr (I < 64) {
;         float a0 = Ll[I * 64 + lane], a1 = 0.f, a2 = 0.f, a3 = 0.f;
;         f32x4 lr[16];
;         s2_load<I, 0>(Ll, lr);
;         s2_fma<I, 0>(lr, Xc, a0, a1, a2, a3);
;         Xc[I] = -((a0 + a1) + (a2 + a3));
;         asm volatile("" ::: "memory");
;         s2_row<I + 1>(Ll, Xc, lane);
;     }
; }
; __device__ __forceinline__ void prep_task(LAS unsigned char* lds, const PrepP& P, int task, int tid, int lane, int wave) {
;     ...
;     if (wave == 0) {
;         float Xc[64];
;         s2_row<0>(Ll, Xc, lane);
; #pragma unroll
;         for (int i = 0; i < 64; ++i) Tl[i * TS + lane] = f2bf(Xc[i]);
;         asm volatile("s_waitcnt lgkmcnt(0)" ::: "memory");
;         Tl[lane * TS + lane] = (bf16_t)0x3F80u;
	v_pk_fma_f32 v[48:49], v[96:97], v[16:17], v[48:49]
	ds_read_b128 v[156:159], v148 offset:11136
	v_pk_fma_f32 v[50:51], v[98:99], v[18:19], v[50:51]
	ds_read_b128 v[160:163], v148 offset:11152
	v_pk_fma_f32 v[48:49], v[100:101], v[20:21], v[48:49]
	ds_read_b128 v[164:167], v148 offset:11168
	v_pk_fma_f32 v[50:51], v[102:103], v[22:23], v[50:51]
	v_pk_fma_f32 v[48:49], v[104:105], v[24:25], v[48:49]
	v_add_f32_e32 v1, v48, v49
	v_add_f32_e32 v2, v50, v51
	v_sub_f32_e64 v106, -v1, v2
	s_waitcnt lgkmcnt(12)
	v_fma_f32 v48, v64, v28, v11
	ds_read2st64_b32 v[52:53], v149 offset0:44 offset1:45
	v_mul_f32_e32 v49, v65, v29
	v_pk_mul_f32 v[50:51], v[66:67], v[30:31]
	s_waitcnt lgkmcnt(8)
	v_pk_fma_f32 v[48:49], v[68:69], v[32:33], v[48:49]
	ds_read_b128 v[168:171], v148 offset:11264
	v_pk_fma_f32 v[50:51], v[70:71], v[34:35], v[50:51]
	ds_read_b128 v[172:175], v148 offset:11280
	v_pk_fma_f32 v[48:49], v[72:73], v[36:37], v[48:49]
	ds_read_b128 v[176:179], v148 offset:11296
	v_pk_fma_f32 v[50:51], v[74:75], v[38:39], v[50:51]
	ds_read_b128 v[180:183], v148 offset:11312
	v_pk_fma_f32 v[48:49], v[76:77], v[128:129], v[48:49]
	ds_read_b128 v[184:187], v148 offset:11328
	v_pk_fma_f32 v[50:51], v[78:79], v[130:131], v[50:51]
	s_waitcnt lgkmcnt(10)
	v_pk_fma_f32 v[48:49], v[80:81], v[132:133], v[48:49]
	ds_read_b128 v[188:191], v148 offset:11344
	v_pk_fma_f32 v[50:51], v[82:83], v[134:135], v[50:51]
	ds_read_b128 v[200:203], v148 offset:11360
	v_pk_fma_f32 v[48:49], v[84:85], v[136:137], v[48:49]
	ds_read_b128 v[204:207], v148 offset:11376
	v_pk_fma_f32 v[50:51], v[86:87], v[138:139], v[50:51]
	v_pk_fma_f32 v[48:49], v[88:89], v[140:141], v[48:49]
	v_pk_fma_f32 v[50:51], v[90:91], v[142:143], v[50:51]
	s_waitcnt lgkmcnt(10)
	v_pk_fma_f32 v[48:49], v[92:93], v[144:145], v[48:49]
	ds_read_b128 v[208:211], v148 offset:11392
	v_pk_fma_f32 v[50:51], v[94:95], v[146:147], v[50:51]
	ds_read_b128 v[212:215], v148 offset:11408
	v_pk_fma_f32 v[48:49], v[96:97], v[156:157], v[48:49]
	ds_read_b128 v[216:219], v148 offset:11424
	v_pk_fma_f32 v[50:51], v[98:99], v[158:159], v[50:51]
	v_pk_fma_f32 v[48:49], v[100:101], v[160:161], v[48:49]
	v_pk_fma_f32 v[50:51], v[102:103], v[162:163], v[50:51]
	s_waitcnt lgkmcnt(12)
	v_pk_fma_f32 v[48:49], v[104:105], v[164:165], v[48:49]
	ds_read_b128 v[220:223], v148 offset:11520
	v_fma_f32 v50, v106, v166, v50
	v_add_f32_e32 v1, v48, v49
	v_add_f32_e32 v2, v50, v51
	v_sub_f32_e64 v107, -v1, v2
	v_cvt_pk_bf16_f32 v3, v106, v107
	ds_write_b16 v150, v3 offset:6048
	ds_write_b16_d16_hi v150, v3 offset:6192
	s_waitcnt lgkmcnt(12)
	v_fma_f32 v48, v64, v168, v52
	ds_read_b128 v[224:227], v148 offset:11536
	v_mul_f32_e32 v49, v65, v169
	v_pk_mul_f32 v[50:51], v[66:67], v[170:171]
	v_pk_fma_f32 v[48:49], v[68:69], v[172:173], v[48:49]
	v_pk_fma_f32 v[50:51], v[70:71], v[174:175], v[50:51]
	s_waitcnt lgkmcnt(10)
	v_pk_fma_f32 v[48:49], v[72:73], v[176:177], v[48:49]
	ds_read_b128 v[228:231], v148 offset:11552
	v_pk_fma_f32 v[50:51], v[74:75], v[178:179], v[50:51]
	ds_read_b128 v[232:235], v148 offset:11568
	v_pk_fma_f32 v[48:49], v[76:77], v[180:181], v[48:49]
	ds_read_b128 v[236:239], v148 offset:11584
	v_pk_fma_f32 v[50:51], v[78:79], v[182:183], v[50:51]
	v_pk_fma_f32 v[48:49], v[80:81], v[184:185], v[48:49]
	v_pk_fma_f32 v[50:51], v[82:83], v[186:187], v[50:51]
	s_waitcnt lgkmcnt(10)
	v_pk_fma_f32 v[48:49], v[84:85], v[188:189], v[48:49]
	ds_read_b128 v[240:243], v148 offset:11600
	v_pk_fma_f32 v[50:51], v[86:87], v[190:191], v[50:51]
	ds_read_b128 v[244:247], v148 offset:11616
	v_pk_fma_f32 v[48:49], v[88:89], v[200:201], v[48:49]
	ds_read_b128 v[248:251], v148 offset:11632
	v_pk_fma_f32 v[50:51], v[90:91], v[202:203], v[50:51]
	v_pk_fma_f32 v[48:49], v[92:93], v[204:205], v[48:49]
	v_pk_fma_f32 v[50:51], v[94:95], v[206:207], v[50:51]
	s_waitcnt lgkmcnt(10)
	v_pk_fma_f32 v[48:49], v[96:97], v[208:209], v[48:49]
	ds_read_b128 v[12:15], v148 offset:11648
	v_pk_fma_f32 v[50:51], v[98:99], v[210:211], v[50:51]
	ds_read_b128 v[16:19], v148 offset:11664
	v_pk_fma_f32 v[48:49], v[100:101], v[212:213], v[48:49]
	ds_read_b128 v[20:23], v148 offset:11680
	v_pk_fma_f32 v[50:51], v[102:103], v[214:215], v[50:51]
	v_pk_fma_f32 v[48:49], v[104:105], v[216:217], v[48:49]
	v_pk_fma_f32 v[50:51], v[106:107], v[218:219], v[50:51]
	v_add_f32_e32 v1, v48, v49
	v_add_f32_e32 v2, v50, v51
	v_sub_f32_e64 v108, -v1, v2
	s_waitcnt lgkmcnt(12)
	v_fma_f32 v48, v64, v220, v53
	ds_read_b128 v[24:27], v148 offset:11696
	v_mul_f32_e32 v49, v65, v221
	v_pk_mul_f32 v[50:51], v[66:67], v[222:223]
	s_waitcnt lgkmcnt(8)
	v_pk_fma_f32 v[48:49], v[68:69], v[224:225], v[48:49]
	ds_read2st64_b32 v[252:253], v149 offset0:46 offset1:47
	v_pk_fma_f32 v[50:51], v[70:71], v[226:227], v[50:51]
	ds_read_b128 v[28:31], v148 offset:11776
	v_pk_fma_f32 v[48:49], v[72:73], v[228:229], v[48:49]
	ds_read_b128 v[32:35], v148 offset:11792
	v_pk_fma_f32 v[50:51], v[74:75], v[230:231], v[50:51]
	ds_read_b128 v[36:39], v148 offset:11808
	v_pk_fma_f32 v[48:49], v[76:77], v[232:233], v[48:49]
	ds_read_b128 v[128:131], v148 offset:11824
	v_pk_fma_f32 v[50:51], v[78:79], v[234:235], v[50:51]
	s_waitcnt lgkmcnt(10)
	v_pk_fma_f32 v[48:49], v[80:81], v[236:237], v[48:49]
	ds_read_b128 v[132:135], v148 offset:11840
	v_pk_fma_f32 v[50:51], v[82:83], v[238:239], v[50:51]
	ds_read_b128 v[136:139], v148 offset:11856
	v_pk_fma_f32 v[48:49], v[84:85], v[240:241], v[48:49]
	ds_read_b128 v[140:143], v148 offset:11872
	v_pk_fma_f32 v[50:51], v[86:87], v[242:243], v[50:51]
	v_pk_fma_f32 v[48:49], v[88:89], v[244:245], v[48:49]
	v_pk_fma_f32 v[50:51], v[90:91], v[246:247], v[50:51]
	s_waitcnt lgkmcnt(10)
; #define LAS __attribute__((address_space(3)))
; __device__ __forceinline__ bf16_t f2bf(float f) { return (bf16_t)(pk2(f, 0.f) & 0xffffu); }
; template <int I, int C> __device__ __forceinline__ void s2_load(const LAS float* Ll, f32x4 (&lr)[16]) {
;     if constexpr (4 * C < I) { lr[C] = *(const LAS f32x4*)(Ll + I * 64 + 4 * C); s2_load<I, C + 1>(Ll, lr); }
; }
; template <int I, int C> __device__ __forceinline__ void s2_fma(const f32x4 (&lr)[16], const float (&Xc)[64], float& a0, float& a1, float& a2, float& a3) {
;     if constexpr (4 * C < I) {
;         a0 += lr[C].x * Xc[4 * C];
;         if constexpr (4 * C + 1 < I) a1 += lr[C].y * Xc[4 * C + 1];
;         if constexpr (4 * C + 2 < I) a2 += lr[C].z * Xc[4 * C + 2];
;         if constexpr (4 * C + 3 < I) a3 += lr[C].w * Xc[4 * C + 3];
;         s2_fma<I, C + 1>(lr, Xc, a0, a1, a2, a3);
;     }
; }
; template <int I> __device__ __forceinline__ void s2_row(const LAS float* Ll, float (&Xc)[64], int lane) {
;     if constexpr (I < 64) {
;         float a0 = Ll[I * 64 + lane], a1 = 0.f, a2 = 0.f, a3 = 0.f;
;         f32x4 lr[16];
;         s2_load<I, 0>(Ll, lr);
;         s2_fma<I, 0>(lr, Xc, a0, a1, a2, a3);
;         Xc[I] = -((a0 + a1) + (a2 + a3));
;         asm volatile("" ::: "memory");
;         s2_row<I + 1>(Ll, Xc, lane);
;     }
; }
; __device__ __forceinline__ void prep_task(LAS unsigned char* lds, const PrepP& P, int task, int tid, int lane, int wave) {
;     ...
;     if (wave == 0) {
;         float Xc[64];
;         s2_row<0>(Ll, Xc, lane);
; #pragma unroll
;         for (int i = 0; i < 64; ++i) Tl[i * TS + lane] = f2bf(Xc[i]);
;         asm volatile("s_waitcnt lgkmcnt(0)" ::: "memory");
;         Tl[lane * TS + lane] = (bf16_t)0x3F80u;
	v_pk_fma_f32 v[48:49], v[92:93], v[248:249], v[48:49]
	ds_read_b128 v[144:147], v148 offset:11888
	v_pk_fma_f32 v[50:51], v[94:95], v[250:251], v[50:51]
	ds_read_b128 v[156:159], v148 offset:11904
	v_pk_fma_f32 v[48:49], v[96:97], v[12:13], v[48:49]
	ds_read_b128 v[160:163], v148 offset:11920
	v_pk_fma_f32 v[50:51], v[98:99], v[14:15], v[50:51]
	v_pk_fma_f32 v[48:49], v[100:101], v[16:17], v[48:49]
	v_pk_fma_f32 v[50:51], v[102:103], v[18:19], v[50:51]
	s_waitcnt lgkmcnt(11)
	v_pk_fma_f32 v[48:49], v[104:105], v[20:21], v[48:49]
	ds_read_b128 v[164:167], v148 offset:11936
	v_pk_fma_f32 v[50:51], v[106:107], v[22:23], v[50:51]
	ds_read_b128 v[168:171], v148 offset:11952
	v_fma_f32 v48, v108, v24, v48
	v_add_f32_e32 v1, v48, v49
	v_add_f32_e32 v2, v50, v51
	v_sub_f32_e64 v109, -v1, v2
	v_cvt_pk_bf16_f32 v3, v108, v109
	ds_write_b16 v150, v3 offset:6336
	ds_write_b16_d16_hi v150, v3 offset:6480
	s_waitcnt lgkmcnt(12)
	v_fma_f32 v48, v64, v28, v252
	ds_read_b128 v[172:175], v148 offset:12032
	v_mul_f32_e32 v49, v65, v29
	v_pk_mul_f32 v[50:51], v[66:67], v[30:31]
	v_pk_fma_f32 v[48:49], v[68:69], v[32:33], v[48:49]
	v_pk_fma_f32 v[50:51], v[70:71], v[34:35], v[50:51]
	s_waitcnt lgkmcnt(10)
	v_pk_fma_f32 v[48:49], v[72:73], v[36:37], v[48:49]
	ds_read_b128 v[176:179], v148 offset:12048
	v_pk_fma_f32 v[50:51], v[74:75], v[38:39], v[50:51]
	ds_read_b128 v[180:183], v148 offset:12064
	v_pk_fma_f32 v[48:49], v[76:77], v[128:129], v[48:49]
	ds_read_b128 v[184:187], v148 offset:12080
	v_pk_fma_f32 v[50:51], v[78:79], v[130:131], v[50:51]
	v_pk_fma_f32 v[48:49], v[80:81], v[132:133], v[48:49]
	v_pk_fma_f32 v[50:51], v[82:83], v[134:135], v[50:51]
	s_waitcnt lgkmcnt(10)
	v_pk_fma_f32 v[48:49], v[84:85], v[136:137], v[48:49]
	ds_read_b128 v[188:191], v148 offset:12096
	v_pk_fma_f32 v[50:51], v[86:87], v[138:139], v[50:51]
	ds_read_b128 v[200:203], v148 offset:12112
	v_pk_fma_f32 v[48:49], v[88:89], v[140:141], v[48:49]
	ds_read_b128 v[204:207], v148 offset:12128
	v_pk_fma_f32 v[50:51], v[90:91], v[142:143], v[50:51]
	v_pk_fma_f32 v[48:49], v[92:93], v[144:145], v[48:49]
	v_pk_fma_f32 v[50:51], v[94:95], v[146:147], v[50:51]
	s_waitcnt lgkmcnt(10)
	v_pk_fma_f32 v[48:49], v[96:97], v[156:157], v[48:49]
	ds_read_b128 v[208:211], v148 offset:12144
	v_pk_fma_f32 v[50:51], v[98:99], v[158:159], v[50:51]
	ds_read_b128 v[212:215], v148 offset:12160
	v_pk_fma_f32 v[48:49], v[100:101], v[160:161], v[48:49]
	ds_read_b128 v[216:219], v148 offset:12176
	v_pk_fma_f32 v[50:51], v[102:103], v[162:163], v[50:51]
	v_pk_fma_f32 v[48:49], v[104:105], v[164:165], v[48:49]
	v_pk_fma_f32 v[50:51], v[106:107], v[166:167], v[50:51]
	s_waitcnt lgkmcnt(12)
	v_pk_fma_f32 v[48:49], v[108:109], v[168:169], v[48:49]
	ds_read_b128 v[220:223], v148 offset:12192
	v_add_f32_e32 v1, v48, v49
	v_add_f32_e32 v2, v50, v51
	v_sub_f32_e64 v110, -v1, v2
	s_waitcnt lgkmcnt(8)
	v_fma_f32 v48, v64, v172, v253
	ds_read_b128 v[224:227], v148 offset:12208
	v_mul_f32_e32 v49, v65, v173
	ds_read2st64_b32 v[4:5], v149 offset0:48 offset1:49
	v_pk_mul_f32 v[50:51], v[66:67], v[174:175]
	ds_read_b128 v[228:231], v148 offset:12288
	v_pk_fma_f32 v[48:49], v[68:69], v[176:177], v[48:49]
	ds_read_b128 v[232:235], v148 offset:12304
	v_pk_fma_f32 v[50:51], v[70:71], v[178:179], v[50:51]
	ds_read_b128 v[236:239], v148 offset:12320
	v_pk_fma_f32 v[48:49], v[72:73], v[180:181], v[48:49]
	v_pk_fma_f32 v[50:51], v[74:75], v[182:183], v[50:51]
	s_waitcnt lgkmcnt(10)
	v_pk_fma_f32 v[48:49], v[76:77], v[184:185], v[48:49]
	ds_read_b128 v[240:243], v148 offset:12336
	v_pk_fma_f32 v[50:51], v[78:79], v[186:187], v[50:51]
	ds_read_b128 v[244:247], v148 offset:12352
	v_pk_fma_f32 v[48:49], v[80:81], v[188:189], v[48:49]
	ds_read_b128 v[248:251], v148 offset:12368
	v_pk_fma_f32 v[50:51], v[82:83], v[190:191], v[50:51]
	v_pk_fma_f32 v[48:49], v[84:85], v[200:201], v[48:49]
	v_pk_fma_f32 v[50:51], v[86:87], v[202:203], v[50:51]
	s_waitcnt lgkmcnt(10)
	v_pk_fma_f32 v[48:49], v[88:89], v[204:205], v[48:49]
	ds_read_b128 v[12:15], v148 offset:12384
	v_pk_fma_f32 v[50:51], v[90:91], v[206:207], v[50:51]
	ds_read_b128 v[16:19], v148 offset:12400
	v_pk_fma_f32 v[48:49], v[92:93], v[208:209], v[48:49]
	ds_read_b128 v[20:23], v148 offset:12416
	v_pk_fma_f32 v[50:51], v[94:95], v[210:211], v[50:51]
	v_pk_fma_f32 v[48:49], v[96:97], v[212:213], v[48:49]
	v_pk_fma_f32 v[50:51], v[98:99], v[214:215], v[50:51]
	s_waitcnt lgkmcnt(10)
	v_pk_fma_f32 v[48:49], v[100:101], v[216:217], v[48:49]
	ds_read_b128 v[24:27], v148 offset:12432
	v_pk_fma_f32 v[50:51], v[102:103], v[218:219], v[50:51]
	ds_read_b128 v[28:31], v148 offset:12448
	v_pk_fma_f32 v[48:49], v[104:105], v[220:221], v[48:49]
	ds_read_b128 v[32:35], v148 offset:12464
	v_pk_fma_f32 v[50:51], v[106:107], v[222:223], v[50:51]
	v_pk_fma_f32 v[48:49], v[108:109], v[224:225], v[48:49]
	v_fma_f32 v50, v110, v226, v50
	v_add_f32_e32 v1, v48, v49
	v_add_f32_e32 v2, v50, v51
	v_sub_f32_e64 v111, -v1, v2
	v_cvt_pk_bf16_f32 v3, v110, v111
	ds_write_b16 v150, v3 offset:6624
	ds_write_b16_d16_hi v150, v3 offset:6768
	s_waitcnt lgkmcnt(12)
	v_fma_f32 v48, v64, v228, v4
	ds_read_b128 v[36:39], v148 offset:12544
	v_mul_f32_e32 v49, v65, v229
	v_pk_mul_f32 v[50:51], v[66:67], v[230:231]
	v_pk_fma_f32 v[48:49], v[68:69], v[232:233], v[48:49]
	v_pk_fma_f32 v[50:51], v[70:71], v[234:235], v[50:51]
	s_waitcnt lgkmcnt(10)
	v_pk_fma_f32 v[48:49], v[72:73], v[236:237], v[48:49]
	ds_read_b128 v[128:131], v148 offset:12560
	v_pk_fma_f32 v[50:51], v[74:75], v[238:239], v[50:51]
	ds_read_b128 v[132:135], v148 offset:12576
	v_pk_fma_f32 v[48:49], v[76:77], v[240:241], v[48:49]
	ds_read_b128 v[136:139], v148 offset:12592
	v_pk_fma_f32 v[50:51], v[78:79], v[242:243], v[50:51]
	v_pk_fma_f32 v[48:49], v[80:81], v[244:245], v[48:49]
	v_pk_fma_f32 v[50:51], v[82:83], v[246:247], v[50:51]
	s_waitcnt lgkmcnt(10)
; #define LAS __attribute__((address_space(3)))
; __device__ __forceinline__ bf16_t f2bf(float f) { return (bf16_t)(pk2(f, 0.f) & 0xffffu); }
; template <int I, int C> __device__ __forceinline__ void s2_load(const LAS float* Ll, f32x4 (&lr)[16]) {
;     if constexpr (4 * C < I) { lr[C] = *(const LAS f32x4*)(Ll + I * 64 + 4 * C); s2_load<I, C + 1>(Ll, lr); }
; }
; template <int I, int C> __device__ __forceinline__ void s2_fma(const f32x4 (&lr)[16], const float (&Xc)[64], float& a0, float& a1, float& a2, float& a3) {
;     if constexpr (4 * C < I) {
;         a0 += lr[C].x * Xc[4 * C];
;         if constexpr (4 * C + 1 < I) a1 += lr[C].y * Xc[4 * C + 1];
;         if constexpr (4 * C + 2 < I) a2 += lr[C].z * Xc[4 * C + 2];
;         if constexpr (4 * C + 3 < I) a3 += lr[C].w * Xc[4 * C + 3];
;         s2_fma<I, C + 1>(lr, Xc, a0, a1, a2, a3);
;     }
; }
; template <int I> __device__ __forceinline__ void s2_row(const LAS float* Ll, float (&Xc)[64], int lane) {
;     if constexpr (I < 64) {
;         float a0 = Ll[I * 64 + lane], a1 = 0.f, a2 = 0.f, a3 = 0.f;
;         f32x4 lr[16];
;         s2_load<I, 0>(Ll, lr);
;         s2_fma<I, 0>(lr, Xc, a0, a1, a2, a3);
;         Xc[I] = -((a0 + a1) + (a2 + a3));
;         asm volatile("" ::: "memory");
;         s2_row<I + 1>(Ll, Xc, lane);
;     }
; }
; __device__ __forceinline__ void prep_task(LAS unsigned char* lds, const PrepP& P, int task, int tid, int lane, int wave) {
;     ...
;     if (wave == 0) {
;         float Xc[64];
;         s2_row<0>(Ll, Xc, lane);
; #pragma unroll
;         for (int i = 0; i < 64; ++i) Tl[i * TS + lane] = f2bf(Xc[i]);
;         asm volatile("s_waitcnt lgkmcnt(0)" ::: "memory");
;         Tl[lane * TS + lane] = (bf16_t)0x3F80u;
	v_pk_fma_f32 v[48:49], v[84:85], v[248:249], v[48:49]
	ds_read_b128 v[140:143], v148 offset:12608
	v_pk_fma_f32 v[50:51], v[86:87], v[250:251], v[50:51]
	ds_read_b128 v[144:147], v148 offset:12624
	v_pk_fma_f32 v[48:49], v[88:89], v[12:13], v[48:49]
	ds_read_b128 v[156:159], v148 offset:12640
	v_pk_fma_f32 v[50:51], v[90:91], v[14:15], v[50:51]
	v_pk_fma_f32 v[48:49], v[92:93], v[16:17], v[48:49]
	v_pk_fma_f32 v[50:51], v[94:95], v[18:19], v[50:51]
	s_waitcnt lgkmcnt(10)
	v_pk_fma_f32 v[48:49], v[96:97], v[20:21], v[48:49]
	ds_read_b128 v[160:163], v148 offset:12656
	v_pk_fma_f32 v[50:51], v[98:99], v[22:23], v[50:51]
	ds_read_b128 v[164:167], v148 offset:12672
	v_pk_fma_f32 v[48:49], v[100:101], v[24:25], v[48:49]
	ds_read_b128 v[168:171], v148 offset:12688
	v_pk_fma_f32 v[50:51], v[102:103], v[26:27], v[50:51]
	v_pk_fma_f32 v[48:49], v[104:105], v[28:29], v[48:49]
	v_pk_fma_f32 v[50:51], v[106:107], v[30:31], v[50:51]
	s_waitcnt lgkmcnt(12)
	v_pk_fma_f32 v[48:49], v[108:109], v[32:33], v[48:49]
	ds_read_b128 v[172:175], v148 offset:12704
	v_pk_fma_f32 v[50:51], v[110:111], v[34:35], v[50:51]
	v_add_f32_e32 v1, v48, v49
	v_add_f32_e32 v2, v50, v51
	v_sub_f32_e64 v112, -v1, v2
	s_waitcnt lgkmcnt(8)
	v_fma_f32 v48, v64, v36, v5
	ds_read_b128 v[176:179], v148 offset:12720
	v_mul_f32_e32 v49, v65, v37
	ds_read_b128 v[180:183], v148 offset:12736
	v_pk_mul_f32 v[50:51], v[66:67], v[38:39]
	ds_read2st64_b32 v[6:7], v149 offset0:50 offset1:51
	v_pk_fma_f32 v[48:49], v[68:69], v[128:129], v[48:49]
	ds_read_b128 v[184:187], v148 offset:12800
	v_pk_fma_f32 v[50:51], v[70:71], v[130:131], v[50:51]
	ds_read_b128 v[188:191], v148 offset:12816
	v_pk_fma_f32 v[48:49], v[72:73], v[132:133], v[48:49]
	v_pk_fma_f32 v[50:51], v[74:75], v[134:135], v[50:51]
	s_waitcnt lgkmcnt(10)
	v_pk_fma_f32 v[48:49], v[76:77], v[136:137], v[48:49]
	ds_read_b128 v[200:203], v148 offset:12832
	v_pk_fma_f32 v[50:51], v[78:79], v[138:139], v[50:51]
	ds_read_b128 v[204:207], v148 offset:12848
	v_pk_fma_f32 v[48:49], v[80:81], v[140:141], v[48:49]
	ds_read_b128 v[208:211], v148 offset:12864
	v_pk_fma_f32 v[50:51], v[82:83], v[142:143], v[50:51]
	v_pk_fma_f32 v[48:49], v[84:85], v[144:145], v[48:49]
	v_pk_fma_f32 v[50:51], v[86:87], v[146:147], v[50:51]
	s_waitcnt lgkmcnt(10)
	v_pk_fma_f32 v[48:49], v[88:89], v[156:157], v[48:49]
	ds_read_b128 v[212:215], v148 offset:12880
	v_pk_fma_f32 v[50:51], v[90:91], v[158:159], v[50:51]
	ds_read_b128 v[216:219], v148 offset:12896
	v_pk_fma_f32 v[48:49], v[92:93], v[160:161], v[48:49]
	ds_read_b128 v[220:223], v148 offset:12912
	v_pk_fma_f32 v[50:51], v[94:95], v[162:163], v[50:51]
	v_pk_fma_f32 v[48:49], v[96:97], v[164:165], v[48:49]
	v_pk_fma_f32 v[50:51], v[98:99], v[166:167], v[50:51]
	s_waitcnt lgkmcnt(10)
	v_pk_fma_f32 v[48:49], v[100:101], v[168:169], v[48:49]
	ds_read_b128 v[224:227], v148 offset:12928
	v_pk_fma_f32 v[50:51], v[102:103], v[170:171], v[50:51]
	ds_read_b128 v[228:231], v148 offset:12944
	v_pk_fma_f32 v[48:49], v[104:105], v[172:173], v[48:49]
	ds_read_b128 v[232:235], v148 offset:12960
	v_pk_fma_f32 v[50:51], v[106:107], v[174:175], v[50:51]
	v_pk_fma_f32 v[48:49], v[108:109], v[176:177], v[48:49]
	v_pk_fma_f32 v[50:51], v[110:111], v[178:179], v[50:51]
	s_waitcnt lgkmcnt(12)
	v_fma_f32 v48, v112, v180, v48
	ds_read_b128 v[236:239], v148 offset:12976
	v_add_f32_e32 v1, v48, v49
	v_add_f32_e32 v2, v50, v51
	v_sub_f32_e64 v113, -v1, v2
	v_cvt_pk_bf16_f32 v3, v112, v113
	ds_write_b16 v150, v3 offset:6912
	ds_write_b16_d16_hi v150, v3 offset:7056
	s_waitcnt lgkmcnt(12)
	v_fma_f32 v48, v64, v184, v6
	ds_read_b128 v[240:243], v148 offset:12992
	v_mul_f32_e32 v49, v65, v185
	v_pk_mul_f32 v[50:51], v[66:67], v[186:187]
	v_pk_fma_f32 v[48:49], v[68:69], v[188:189], v[48:49]
	v_pk_fma_f32 v[50:51], v[70:71], v[190:191], v[50:51]
	s_waitcnt lgkmcnt(10)
	v_pk_fma_f32 v[48:49], v[72:73], v[200:201], v[48:49]
	ds_read_b128 v[244:247], v148 offset:13056
	v_pk_fma_f32 v[50:51], v[74:75], v[202:203], v[50:51]
	ds_read_b128 v[248:251], v148 offset:13072
	v_pk_fma_f32 v[48:49], v[76:77], v[204:205], v[48:49]
	ds_read_b128 v[12:15], v148 offset:13088
	v_pk_fma_f32 v[50:51], v[78:79], v[206:207], v[50:51]
	v_pk_fma_f32 v[48:49], v[80:81], v[208:209], v[48:49]
	v_pk_fma_f32 v[50:51], v[82:83], v[210:211], v[50:51]
	s_waitcnt lgkmcnt(10)
	v_pk_fma_f32 v[48:49], v[84:85], v[212:213], v[48:49]
	ds_read_b128 v[16:19], v148 offset:13104
	v_pk_fma_f32 v[50:51], v[86:87], v[214:215], v[50:51]
	ds_read_b128 v[20:23], v148 offset:13120
	v_pk_fma_f32 v[48:49], v[88:89], v[216:217], v[48:49]
	ds_read_b128 v[24:27], v148 offset:13136
	v_pk_fma_f32 v[50:51], v[90:91], v[218:219], v[50:51]
	v_pk_fma_f32 v[48:49], v[92:93], v[220:221], v[48:49]
	v_pk_fma_f32 v[50:51], v[94:95], v[222:223], v[50:51]
	s_waitcnt lgkmcnt(10)
	v_pk_fma_f32 v[48:49], v[96:97], v[224:225], v[48:49]
	ds_read_b128 v[28:31], v148 offset:13152
	v_pk_fma_f32 v[50:51], v[98:99], v[226:227], v[50:51]
	ds_read_b128 v[32:35], v148 offset:13168
	v_pk_fma_f32 v[48:49], v[100:101], v[228:229], v[48:49]
	ds_read_b128 v[36:39], v148 offset:13184
	v_pk_fma_f32 v[50:51], v[102:103], v[230:231], v[50:51]
	v_pk_fma_f32 v[48:49], v[104:105], v[232:233], v[48:49]
	v_pk_fma_f32 v[50:51], v[106:107], v[234:235], v[50:51]
	s_waitcnt lgkmcnt(12)
	v_pk_fma_f32 v[48:49], v[108:109], v[236:237], v[48:49]
	ds_read_b128 v[128:131], v148 offset:13200
	v_pk_fma_f32 v[50:51], v[110:111], v[238:239], v[50:51]
	s_waitcnt lgkmcnt(10)
	v_pk_fma_f32 v[48:49], v[112:113], v[240:241], v[48:49]
	ds_read_b128 v[132:135], v148 offset:13216
	v_add_f32_e32 v1, v48, v49
	ds_read_b128 v[136:139], v148 offset:13232
	v_add_f32_e32 v2, v50, v51
	ds_read_b128 v[140:143], v148 offset:13248
	v_sub_f32_e64 v114, -v1, v2
	s_waitcnt lgkmcnt(10)
; #define LAS __attribute__((address_space(3)))
; __device__ __forceinline__ bf16_t f2bf(float f) { return (bf16_t)(pk2(f, 0.f) & 0xffffu); }
; template <int I, int C> __device__ __forceinline__ void s2_load(const LAS float* Ll, f32x4 (&lr)[16]) {
;     if constexpr (4 * C < I) { lr[C] = *(const LAS f32x4*)(Ll + I * 64 + 4 * C); s2_load<I, C + 1>(Ll, lr); }
; }
; template <int I, int C> __device__ __forceinline__ void s2_fma(const f32x4 (&lr)[16], const float (&Xc)[64], float& a0, float& a1, float& a2, float& a3) {
;     if constexpr (4 * C < I) {
;         a0 += lr[C].x * Xc[4 * C];
;         if constexpr (4 * C + 1 < I) a1 += lr[C].y * Xc[4 * C + 1];
;         if constexpr (4 * C + 2 < I) a2 += lr[C].z * Xc[4 * C + 2];
;         if constexpr (4 * C + 3 < I) a3 += lr[C].w * Xc[4 * C + 3];
;         s2_fma<I, C + 1>(lr, Xc, a0, a1, a2, a3);
;     }
; }
; template <int I> __device__ __forceinline__ void s2_row(const LAS float* Ll, float (&Xc)[64], int lane) {
;     if constexpr (I < 64) {
;         float a0 = Ll[I * 64 + lane], a1 = 0.f, a2 = 0.f, a3 = 0.f;
;         f32x4 lr[16];
;         s2_load<I, 0>(Ll, lr);
;         s2_fma<I, 0>(lr, Xc, a0, a1, a2, a3);
;         Xc[I] = -((a0 + a1) + (a2 + a3));
;         asm volatile("" ::: "memory");
;         s2_row<I + 1>(Ll, Xc, lane);
;     }
; }
; __device__ __forceinline__ void prep_task(LAS unsigned char* lds, const PrepP& P, int task, int tid, int lane, int wave) {
;     ...
;     if (wave == 0) {
;         float Xc[64];
;         s2_row<0>(Ll, Xc, lane);
; #pragma unroll
;         for (int i = 0; i < 64; ++i) Tl[i * TS + lane] = f2bf(Xc[i]);
;         asm volatile("s_waitcnt lgkmcnt(0)" ::: "memory");
;         Tl[lane * TS + lane] = (bf16_t)0x3F80u;
	v_fma_f32 v48, v64, v244, v7
	ds_read2st64_b32 v[8:9], v149 offset0:52 offset1:53
	v_mul_f32_e32 v49, v65, v245
	ds_read_b128 v[144:147], v148 offset:13312
	v_pk_mul_f32 v[50:51], v[66:67], v[246:247]
	ds_read_b128 v[156:159], v148 offset:13328
	v_pk_fma_f32 v[48:49], v[68:69], v[248:249], v[48:49]
	v_pk_fma_f32 v[50:51], v[70:71], v[250:251], v[50:51]
	v_pk_fma_f32 v[48:49], v[72:73], v[12:13], v[48:49]
	v_pk_fma_f32 v[50:51], v[74:75], v[14:15], v[50:51]
	s_waitcnt lgkmcnt(10)
	v_pk_fma_f32 v[48:49], v[76:77], v[16:17], v[48:49]
	ds_read_b128 v[160:163], v148 offset:13344
	v_pk_fma_f32 v[50:51], v[78:79], v[18:19], v[50:51]
	ds_read_b128 v[164:167], v148 offset:13360
	v_pk_fma_f32 v[48:49], v[80:81], v[20:21], v[48:49]
	ds_read_b128 v[168:171], v148 offset:13376
	v_pk_fma_f32 v[50:51], v[82:83], v[22:23], v[50:51]
	v_pk_fma_f32 v[48:49], v[84:85], v[24:25], v[48:49]
	v_pk_fma_f32 v[50:51], v[86:87], v[26:27], v[50:51]
	s_waitcnt lgkmcnt(10)
	v_pk_fma_f32 v[48:49], v[88:89], v[28:29], v[48:49]
	ds_read_b128 v[172:175], v148 offset:13392
	v_pk_fma_f32 v[50:51], v[90:91], v[30:31], v[50:51]
	ds_read_b128 v[176:179], v148 offset:13408
	v_pk_fma_f32 v[48:49], v[92:93], v[32:33], v[48:49]
	ds_read_b128 v[180:183], v148 offset:13424
	v_pk_fma_f32 v[50:51], v[94:95], v[34:35], v[50:51]
	v_pk_fma_f32 v[48:49], v[96:97], v[36:37], v[48:49]
	v_pk_fma_f32 v[50:51], v[98:99], v[38:39], v[50:51]
	s_waitcnt lgkmcnt(10)
	v_pk_fma_f32 v[48:49], v[100:101], v[128:129], v[48:49]
	ds_read_b128 v[184:187], v148 offset:13440
	v_pk_fma_f32 v[50:51], v[102:103], v[130:131], v[50:51]
	ds_read_b128 v[188:191], v148 offset:13456
	v_pk_fma_f32 v[48:49], v[104:105], v[132:133], v[48:49]
	ds_read_b128 v[200:203], v148 offset:13472
	v_pk_fma_f32 v[50:51], v[106:107], v[134:135], v[50:51]
	v_pk_fma_f32 v[48:49], v[108:109], v[136:137], v[48:49]
	v_pk_fma_f32 v[50:51], v[110:111], v[138:139], v[50:51]
	s_waitcnt lgkmcnt(12)
	v_pk_fma_f32 v[48:49], v[112:113], v[140:141], v[48:49]
	ds_read_b128 v[204:207], v148 offset:13488
	v_fma_f32 v50, v114, v142, v50
	v_add_f32_e32 v1, v48, v49
	v_add_f32_e32 v2, v50, v51
	v_sub_f32_e64 v115, -v1, v2
	v_cvt_pk_bf16_f32 v3, v114, v115
	ds_write_b16 v150, v3 offset:7200
	ds_write_b16_d16_hi v150, v3 offset:7344
	s_waitcnt lgkmcnt(12)
	v_fma_f32 v48, v64, v144, v8
	ds_read_b128 v[208:211], v148 offset:13504
	v_mul_f32_e32 v49, v65, v145
	v_pk_mul_f32 v[50:51], v[66:67], v[146:147]
	v_pk_fma_f32 v[48:49], v[68:69], v[156:157], v[48:49]
	v_pk_fma_f32 v[50:51], v[70:71], v[158:159], v[50:51]
	s_waitcnt lgkmcnt(10)
	v_pk_fma_f32 v[48:49], v[72:73], v[160:161], v[48:49]
	ds_read_b128 v[212:215], v148 offset:13568
	v_pk_fma_f32 v[50:51], v[74:75], v[162:163], v[50:51]
	ds_read_b128 v[216:219], v148 offset:13584
	v_pk_fma_f32 v[48:49], v[76:77], v[164:165], v[48:49]
	ds_read_b128 v[220:223], v148 offset:13600
	v_pk_fma_f32 v[50:51], v[78:79], v[166:167], v[50:51]
	v_pk_fma_f32 v[48:49], v[80:81], v[168:169], v[48:49]
	v_pk_fma_f32 v[50:51], v[82:83], v[170:171], v[50:51]
	s_waitcnt lgkmcnt(10)
	v_pk_fma_f32 v[48:49], v[84:85], v[172:173], v[48:49]
	ds_read_b128 v[224:227], v148 offset:13616
	v_pk_fma_f32 v[50:51], v[86:87], v[174:175], v[50:51]
	ds_read_b128 v[228:231], v148 offset:13632
	v_pk_fma_f32 v[48:49], v[88:89], v[176:177], v[48:49]
	ds_read_b128 v[232:235], v148 offset:13648
	v_pk_fma_f32 v[50:51], v[90:91], v[178:179], v[50:51]
	v_pk_fma_f32 v[48:49], v[92:93], v[180:181], v[48:49]
	v_pk_fma_f32 v[50:51], v[94:95], v[182:183], v[50:51]
	s_waitcnt lgkmcnt(10)
	v_pk_fma_f32 v[48:49], v[96:97], v[184:185], v[48:49]
	ds_read_b128 v[236:239], v148 offset:13664
	v_pk_fma_f32 v[50:51], v[98:99], v[186:187], v[50:51]
	ds_read_b128 v[240:243], v148 offset:13680
	v_pk_fma_f32 v[48:49], v[100:101], v[188:189], v[48:49]
	ds_read_b128 v[244:247], v148 offset:13696
	v_pk_fma_f32 v[50:51], v[102:103], v[190:191], v[50:51]
	v_pk_fma_f32 v[48:49], v[104:105], v[200:201], v[48:49]
	v_pk_fma_f32 v[50:51], v[106:107], v[202:203], v[50:51]
	s_waitcnt lgkmcnt(12)
	v_pk_fma_f32 v[48:49], v[108:109], v[204:205], v[48:49]
	ds_read_b128 v[248:251], v148 offset:13712
	v_pk_fma_f32 v[50:51], v[110:111], v[206:207], v[50:51]
	s_waitcnt lgkmcnt(10)
	v_pk_fma_f32 v[48:49], v[112:113], v[208:209], v[48:49]
	ds_read_b128 v[12:15], v148 offset:13728
	v_pk_fma_f32 v[50:51], v[114:115], v[210:211], v[50:51]
	ds_read_b128 v[16:19], v148 offset:13744
	v_add_f32_e32 v1, v48, v49
	ds_read_b128 v[20:23], v148 offset:13760
	v_add_f32_e32 v2, v50, v51
	v_sub_f32_e64 v116, -v1, v2
	s_waitcnt lgkmcnt(10)
	v_fma_f32 v48, v64, v212, v9
	ds_read_b128 v[24:27], v148 offset:13776
	v_mul_f32_e32 v49, v65, v213
	ds_read2st64_b32 v[10:11], v149 offset0:54 offset1:55
	v_pk_mul_f32 v[50:51], v[66:67], v[214:215]
	ds_read_b128 v[28:31], v148 offset:13824
	v_pk_fma_f32 v[48:49], v[68:69], v[216:217], v[48:49]
	v_pk_fma_f32 v[50:51], v[70:71], v[218:219], v[50:51]
	v_pk_fma_f32 v[48:49], v[72:73], v[220:221], v[48:49]
	v_pk_fma_f32 v[50:51], v[74:75], v[222:223], v[50:51]
	s_waitcnt lgkmcnt(10)
	v_pk_fma_f32 v[48:49], v[76:77], v[224:225], v[48:49]
	ds_read_b128 v[32:35], v148 offset:13840
	v_pk_fma_f32 v[50:51], v[78:79], v[226:227], v[50:51]
	ds_read_b128 v[36:39], v148 offset:13856
	v_pk_fma_f32 v[48:49], v[80:81], v[228:229], v[48:49]
	ds_read_b128 v[128:131], v148 offset:13872
	v_pk_fma_f32 v[50:51], v[82:83], v[230:231], v[50:51]
	v_pk_fma_f32 v[48:49], v[84:85], v[232:233], v[48:49]
	v_pk_fma_f32 v[50:51], v[86:87], v[234:235], v[50:51]
	s_waitcnt lgkmcnt(10)
; #define LAS __attribute__((address_space(3)))
; __device__ __forceinline__ bf16_t f2bf(float f) { return (bf16_t)(pk2(f, 0.f) & 0xffffu); }
; template <int I, int C> __device__ __forceinline__ void s2_load(const LAS float* Ll, f32x4 (&lr)[16]) {
;     if constexpr (4 * C < I) { lr[C] = *(const LAS f32x4*)(Ll + I * 64 + 4 * C); s2_load<I, C + 1>(Ll, lr); }
; }
; template <int I, int C> __device__ __forceinline__ void s2_fma(const f32x4 (&lr)[16], const float (&Xc)[64], float& a0, float& a1, float& a2, float& a3) {
;     if constexpr (4 * C < I) {
;         a0 += lr[C].x * Xc[4 * C];
;         if constexpr (4 * C + 1 < I) a1 += lr[C].y * Xc[4 * C + 1];
;         if constexpr (4 * C + 2 < I) a2 += lr[C].z * Xc[4 * C + 2];
;         if constexpr (4 * C + 3 < I) a3 += lr[C].w * Xc[4 * C + 3];
;         s2_fma<I, C + 1>(lr, Xc, a0, a1, a2, a3);
;     }
; }
; template <int I> __device__ __forceinline__ void s2_row(const LAS float* Ll, float (&Xc)[64], int lane) {
;     if constexpr (I < 64) {
;         float a0 = Ll[I * 64 + lane], a1 = 0.f, a2 = 0.f, a3 = 0.f;
;         f32x4 lr[16];
;         s2_load<I, 0>(Ll, lr);
;         s2_fma<I, 0>(lr, Xc, a0, a1, a2, a3);
;         Xc[I] = -((a0 + a1) + (a2 + a3));
;         asm volatile("" ::: "memory");
;         s2_row<I + 1>(Ll, Xc, lane);
;     }
; }
; __device__ __forceinline__ void prep_task(LAS unsigned char* lds, const PrepP& P, int task, int tid, int lane, int wave) {
;     ...
;     if (wave == 0) {
;         float Xc[64];
;         s2_row<0>(Ll, Xc, lane);
; #pragma unroll
;         for (int i = 0; i < 64; ++i) Tl[i * TS + lane] = f2bf(Xc[i]);
;         asm volatile("s_waitcnt lgkmcnt(0)" ::: "memory");
;         Tl[lane * TS + lane] = (bf16_t)0x3F80u;
	v_pk_fma_f32 v[48:49], v[88:89], v[236:237], v[48:49]
	ds_read_b128 v[132:135], v148 offset:13888
	v_pk_fma_f32 v[50:51], v[90:91], v[238:239], v[50:51]
	ds_read_b128 v[136:139], v148 offset:13904
	v_pk_fma_f32 v[48:49], v[92:93], v[240:241], v[48:49]
	ds_read_b128 v[140:143], v148 offset:13920
	v_pk_fma_f32 v[50:51], v[94:95], v[242:243], v[50:51]
	v_pk_fma_f32 v[48:49], v[96:97], v[244:245], v[48:49]
	v_pk_fma_f32 v[50:51], v[98:99], v[246:247], v[50:51]
	s_waitcnt lgkmcnt(10)
	v_pk_fma_f32 v[48:49], v[100:101], v[248:249], v[48:49]
	ds_read_b128 v[144:147], v148 offset:13936
	v_pk_fma_f32 v[50:51], v[102:103], v[250:251], v[50:51]
	ds_read_b128 v[156:159], v148 offset:13952
	v_pk_fma_f32 v[48:49], v[104:105], v[12:13], v[48:49]
	ds_read_b128 v[160:163], v148 offset:13968
	v_pk_fma_f32 v[50:51], v[106:107], v[14:15], v[50:51]
	v_pk_fma_f32 v[48:49], v[108:109], v[16:17], v[48:49]
	v_pk_fma_f32 v[50:51], v[110:111], v[18:19], v[50:51]
	s_waitcnt lgkmcnt(11)
	v_pk_fma_f32 v[48:49], v[112:113], v[20:21], v[48:49]
	ds_read_b128 v[164:167], v148 offset:13984
	v_pk_fma_f32 v[50:51], v[114:115], v[22:23], v[50:51]
	ds_read_b128 v[168:171], v148 offset:14000
	v_fma_f32 v48, v116, v24, v48
	v_add_f32_e32 v1, v48, v49
	v_add_f32_e32 v2, v50, v51
	v_sub_f32_e64 v117, -v1, v2
	v_cvt_pk_bf16_f32 v3, v116, v117
	ds_write_b16 v150, v3 offset:7488
	ds_write_b16_d16_hi v150, v3 offset:7632
	s_waitcnt lgkmcnt(12)
	v_fma_f32 v48, v64, v28, v10
	ds_read_b128 v[172:175], v148 offset:14016
	v_mul_f32_e32 v49, v65, v29
	v_pk_mul_f32 v[50:51], v[66:67], v[30:31]
	v_pk_fma_f32 v[48:49], v[68:69], v[32:33], v[48:49]
	v_pk_fma_f32 v[50:51], v[70:71], v[34:35], v[50:51]
	s_waitcnt lgkmcnt(10)
	v_pk_fma_f32 v[48:49], v[72:73], v[36:37], v[48:49]
	ds_read_b128 v[176:179], v148 offset:14032
	v_pk_fma_f32 v[50:51], v[74:75], v[38:39], v[50:51]
	ds_read_b128 v[180:183], v148 offset:14080
	v_pk_fma_f32 v[48:49], v[76:77], v[128:129], v[48:49]
	ds_read_b128 v[184:187], v148 offset:14096
	v_pk_fma_f32 v[50:51], v[78:79], v[130:131], v[50:51]
	v_pk_fma_f32 v[48:49], v[80:81], v[132:133], v[48:49]
	v_pk_fma_f32 v[50:51], v[82:83], v[134:135], v[50:51]
	s_waitcnt lgkmcnt(10)
	v_pk_fma_f32 v[48:49], v[84:85], v[136:137], v[48:49]
	ds_read_b128 v[188:191], v148 offset:14112
	v_pk_fma_f32 v[50:51], v[86:87], v[138:139], v[50:51]
	ds_read_b128 v[200:203], v148 offset:14128
	v_pk_fma_f32 v[48:49], v[88:89], v[140:141], v[48:49]
	ds_read_b128 v[204:207], v148 offset:14144
	v_pk_fma_f32 v[50:51], v[90:91], v[142:143], v[50:51]
	v_pk_fma_f32 v[48:49], v[92:93], v[144:145], v[48:49]
	v_pk_fma_f32 v[50:51], v[94:95], v[146:147], v[50:51]
	s_waitcnt lgkmcnt(10)
	v_pk_fma_f32 v[48:49], v[96:97], v[156:157], v[48:49]
	ds_read_b128 v[208:211], v148 offset:14160
	v_pk_fma_f32 v[50:51], v[98:99], v[158:159], v[50:51]
	ds_read_b128 v[212:215], v148 offset:14176
	v_pk_fma_f32 v[48:49], v[100:101], v[160:161], v[48:49]
	ds_read_b128 v[216:219], v148 offset:14192
	v_pk_fma_f32 v[50:51], v[102:103], v[162:163], v[50:51]
	v_pk_fma_f32 v[48:49], v[104:105], v[164:165], v[48:49]
	v_pk_fma_f32 v[50:51], v[106:107], v[166:167], v[50:51]
	s_waitcnt lgkmcnt(12)
	v_pk_fma_f32 v[48:49], v[108:109], v[168:169], v[48:49]
	ds_read_b128 v[220:223], v148 offset:14208
	v_pk_fma_f32 v[50:51], v[110:111], v[170:171], v[50:51]
	s_waitcnt lgkmcnt(9)
	v_pk_fma_f32 v[48:49], v[112:113], v[172:173], v[48:49]
	ds_read_b128 v[224:227], v148 offset:14224
	v_pk_fma_f32 v[50:51], v[114:115], v[174:175], v[50:51]
	ds_read_b128 v[228:231], v148 offset:14240
	v_pk_fma_f32 v[48:49], v[116:117], v[176:177], v[48:49]
	ds_read_b128 v[232:235], v148 offset:14256
	v_add_f32_e32 v1, v48, v49
	ds_read_b128 v[236:239], v148 offset:14272
	v_add_f32_e32 v2, v50, v51
	v_sub_f32_e64 v118, -v1, v2
	s_waitcnt lgkmcnt(10)
	v_fma_f32 v48, v64, v180, v11
	ds_read_b128 v[240:243], v148 offset:14288
	v_mul_f32_e32 v49, v65, v181
	ds_read2st64_b32 v[52:53], v149 offset0:56 offset1:57
	v_pk_mul_f32 v[50:51], v[66:67], v[182:183]
	ds_read_b128 v[244:247], v148 offset:14336
	v_pk_fma_f32 v[48:49], v[68:69], v[184:185], v[48:49]
	v_pk_fma_f32 v[50:51], v[70:71], v[186:187], v[50:51]
	v_pk_fma_f32 v[48:49], v[72:73], v[188:189], v[48:49]
	v_pk_fma_f32 v[50:51], v[74:75], v[190:191], v[50:51]
	s_waitcnt lgkmcnt(10)
	v_pk_fma_f32 v[48:49], v[76:77], v[200:201], v[48:49]
	ds_read_b128 v[248:251], v148 offset:14352
	v_pk_fma_f32 v[50:51], v[78:79], v[202:203], v[50:51]
	ds_read_b128 v[12:15], v148 offset:14368
	v_pk_fma_f32 v[48:49], v[80:81], v[204:205], v[48:49]
	ds_read_b128 v[16:19], v148 offset:14384
	v_pk_fma_f32 v[50:51], v[82:83], v[206:207], v[50:51]
	v_pk_fma_f32 v[48:49], v[84:85], v[208:209], v[48:49]
	v_pk_fma_f32 v[50:51], v[86:87], v[210:211], v[50:51]
	s_waitcnt lgkmcnt(10)
	v_pk_fma_f32 v[48:49], v[88:89], v[212:213], v[48:49]
	ds_read_b128 v[20:23], v148 offset:14400
	v_pk_fma_f32 v[50:51], v[90:91], v[214:215], v[50:51]
	ds_read_b128 v[24:27], v148 offset:14416
	v_pk_fma_f32 v[48:49], v[92:93], v[216:217], v[48:49]
	ds_read_b128 v[28:31], v148 offset:14432
	v_pk_fma_f32 v[50:51], v[94:95], v[218:219], v[50:51]
	v_pk_fma_f32 v[48:49], v[96:97], v[220:221], v[48:49]
	v_pk_fma_f32 v[50:51], v[98:99], v[222:223], v[50:51]
	s_waitcnt lgkmcnt(10)
	v_pk_fma_f32 v[48:49], v[100:101], v[224:225], v[48:49]
	ds_read_b128 v[32:35], v148 offset:14448
	v_pk_fma_f32 v[50:51], v[102:103], v[226:227], v[50:51]
	ds_read_b128 v[36:39], v148 offset:14464
	v_pk_fma_f32 v[48:49], v[104:105], v[228:229], v[48:49]
	ds_read_b128 v[128:131], v148 offset:14480
	v_pk_fma_f32 v[50:51], v[106:107], v[230:231], v[50:51]
	v_pk_fma_f32 v[48:49], v[108:109], v[232:233], v[48:49]
	v_pk_fma_f32 v[50:51], v[110:111], v[234:235], v[50:51]
	s_waitcnt lgkmcnt(11)
; #define LAS __attribute__((address_space(3)))
; __device__ __forceinline__ bf16_t f2bf(float f) { return (bf16_t)(pk2(f, 0.f) & 0xffffu); }
; template <int I, int C> __device__ __forceinline__ void s2_load(const LAS float* Ll, f32x4 (&lr)[16]) {
;     if constexpr (4 * C < I) { lr[C] = *(const LAS f32x4*)(Ll + I * 64 + 4 * C); s2_load<I, C + 1>(Ll, lr); }
; }
; template <int I, int C> __device__ __forceinline__ void s2_fma(const f32x4 (&lr)[16], const float (&Xc)[64], float& a0, float& a1, float& a2, float& a3) {
;     if constexpr (4 * C < I) {
;         a0 += lr[C].x * Xc[4 * C];
;         if constexpr (4 * C + 1 < I) a1 += lr[C].y * Xc[4 * C + 1];
;         if constexpr (4 * C + 2 < I) a2 += lr[C].z * Xc[4 * C + 2];
;         if constexpr (4 * C + 3 < I) a3 += lr[C].w * Xc[4 * C + 3];
;         s2_fma<I, C + 1>(lr, Xc, a0, a1, a2, a3);
;     }
; }
; template <int I> __device__ __forceinline__ void s2_row(const LAS float* Ll, float (&Xc)[64], int lane) {
;     if constexpr (I < 64) {
;         float a0 = Ll[I * 64 + lane], a1 = 0.f, a2 = 0.f, a3 = 0.f;
;         f32x4 lr[16];
;         s2_load<I, 0>(Ll, lr);
;         s2_fma<I, 0>(lr, Xc, a0, a1, a2, a3);
;         Xc[I] = -((a0 + a1) + (a2 + a3));
;         asm volatile("" ::: "memory");
;         s2_row<I + 1>(Ll, Xc, lane);
;     }
; }
; __device__ __forceinline__ void prep_task(LAS unsigned char* lds, const PrepP& P, int task, int tid, int lane, int wave) {
;     ...
;     if (wave == 0) {
;         float Xc[64];
;         s2_row<0>(Ll, Xc, lane);
; #pragma unroll
;         for (int i = 0; i < 64; ++i) Tl[i * TS + lane] = f2bf(Xc[i]);
;         asm volatile("s_waitcnt lgkmcnt(0)" ::: "memory");
;         Tl[lane * TS + lane] = (bf16_t)0x3F80u;
	v_pk_fma_f32 v[48:49], v[112:113], v[236:237], v[48:49]
	ds_read_b128 v[132:135], v148 offset:14496
	v_pk_fma_f32 v[50:51], v[114:115], v[238:239], v[50:51]
	ds_read_b128 v[136:139], v148 offset:14512
	v_pk_fma_f32 v[48:49], v[116:117], v[240:241], v[48:49]
	v_fma_f32 v50, v118, v242, v50
	v_add_f32_e32 v1, v48, v49
	v_add_f32_e32 v2, v50, v51
	v_sub_f32_e64 v119, -v1, v2
	v_cvt_pk_bf16_f32 v3, v118, v119
	ds_write_b16 v150, v3 offset:7776
	ds_write_b16_d16_hi v150, v3 offset:7920
	s_waitcnt lgkmcnt(12)
	v_fma_f32 v48, v64, v244, v52
	ds_read_b128 v[140:143], v148 offset:14528
	v_mul_f32_e32 v49, v65, v245
	v_pk_mul_f32 v[50:51], v[66:67], v[246:247]
	v_pk_fma_f32 v[48:49], v[68:69], v[248:249], v[48:49]
	v_pk_fma_f32 v[50:51], v[70:71], v[250:251], v[50:51]
	s_waitcnt lgkmcnt(10)
	v_pk_fma_f32 v[48:49], v[72:73], v[12:13], v[48:49]
	ds_read_b128 v[144:147], v148 offset:14544
	v_pk_fma_f32 v[50:51], v[74:75], v[14:15], v[50:51]
	ds_read_b128 v[156:159], v148 offset:14592
	v_pk_fma_f32 v[48:49], v[76:77], v[16:17], v[48:49]
	ds_read_b128 v[160:163], v148 offset:14608
	v_pk_fma_f32 v[50:51], v[78:79], v[18:19], v[50:51]
	v_pk_fma_f32 v[48:49], v[80:81], v[20:21], v[48:49]
	v_pk_fma_f32 v[50:51], v[82:83], v[22:23], v[50:51]
	s_waitcnt lgkmcnt(10)
	v_pk_fma_f32 v[48:49], v[84:85], v[24:25], v[48:49]
	ds_read_b128 v[164:167], v148 offset:14624
	v_pk_fma_f32 v[50:51], v[86:87], v[26:27], v[50:51]
	ds_read_b128 v[168:171], v148 offset:14640
	v_pk_fma_f32 v[48:49], v[88:89], v[28:29], v[48:49]
	ds_read_b128 v[172:175], v148 offset:14656
	v_pk_fma_f32 v[50:51], v[90:91], v[30:31], v[50:51]
	v_pk_fma_f32 v[48:49], v[92:93], v[32:33], v[48:49]
	v_pk_fma_f32 v[50:51], v[94:95], v[34:35], v[50:51]
	s_waitcnt lgkmcnt(10)
	v_pk_fma_f32 v[48:49], v[96:97], v[36:37], v[48:49]
	ds_read_b128 v[176:179], v148 offset:14672
	v_pk_fma_f32 v[50:51], v[98:99], v[38:39], v[50:51]
	ds_read_b128 v[180:183], v148 offset:14688
	v_pk_fma_f32 v[48:49], v[100:101], v[128:129], v[48:49]
	ds_read_b128 v[184:187], v148 offset:14704
	v_pk_fma_f32 v[50:51], v[102:103], v[130:131], v[50:51]
	v_pk_fma_f32 v[48:49], v[104:105], v[132:133], v[48:49]
	v_pk_fma_f32 v[50:51], v[106:107], v[134:135], v[50:51]
	s_waitcnt lgkmcnt(12)
	v_pk_fma_f32 v[48:49], v[108:109], v[136:137], v[48:49]
	ds_read_b128 v[188:191], v148 offset:14720
	v_pk_fma_f32 v[50:51], v[110:111], v[138:139], v[50:51]
	s_waitcnt lgkmcnt(9)
	v_pk_fma_f32 v[48:49], v[112:113], v[140:141], v[48:49]
	ds_read_b128 v[200:203], v148 offset:14736
	v_pk_fma_f32 v[50:51], v[114:115], v[142:143], v[50:51]
	ds_read_b128 v[204:207], v148 offset:14752
	v_pk_fma_f32 v[48:49], v[116:117], v[144:145], v[48:49]
	ds_read_b128 v[208:211], v148 offset:14768
	v_pk_fma_f32 v[50:51], v[118:119], v[146:147], v[50:51]
	ds_read_b128 v[212:215], v148 offset:14784
	v_add_f32_e32 v1, v48, v49
	v_add_f32_e32 v2, v50, v51
	v_sub_f32_e64 v120, -v1, v2
	s_waitcnt lgkmcnt(10)
	v_fma_f32 v48, v64, v156, v53
	ds_read_b128 v[216:219], v148 offset:14800
	v_mul_f32_e32 v49, v65, v157
	ds_read_b128 v[220:223], v148 offset:14816
	v_pk_mul_f32 v[50:51], v[66:67], v[158:159]
	ds_read2st64_b32 v[252:253], v149 offset0:58 offset1:59
	v_pk_fma_f32 v[48:49], v[68:69], v[160:161], v[48:49]
	v_pk_fma_f32 v[50:51], v[70:71], v[162:163], v[50:51]
	v_pk_fma_f32 v[48:49], v[72:73], v[164:165], v[48:49]
	v_pk_fma_f32 v[50:51], v[74:75], v[166:167], v[50:51]
	s_waitcnt lgkmcnt(10)
	v_pk_fma_f32 v[48:49], v[76:77], v[168:169], v[48:49]
	ds_read_b128 v[224:227], v148 offset:14848
	v_pk_fma_f32 v[50:51], v[78:79], v[170:171], v[50:51]
	ds_read_b128 v[228:231], v148 offset:14864
	v_pk_fma_f32 v[48:49], v[80:81], v[172:173], v[48:49]
	ds_read_b128 v[232:235], v148 offset:14880
	v_pk_fma_f32 v[50:51], v[82:83], v[174:175], v[50:51]
	v_pk_fma_f32 v[48:49], v[84:85], v[176:177], v[48:49]
	v_pk_fma_f32 v[50:51], v[86:87], v[178:179], v[50:51]
	s_waitcnt lgkmcnt(10)
	v_pk_fma_f32 v[48:49], v[88:89], v[180:181], v[48:49]
	ds_read_b128 v[236:239], v148 offset:14896
	v_pk_fma_f32 v[50:51], v[90:91], v[182:183], v[50:51]
	ds_read_b128 v[240:243], v148 offset:14912
	v_pk_fma_f32 v[48:49], v[92:93], v[184:185], v[48:49]
	ds_read_b128 v[244:247], v148 offset:14928
	v_pk_fma_f32 v[50:51], v[94:95], v[186:187], v[50:51]
	v_pk_fma_f32 v[48:49], v[96:97], v[188:189], v[48:49]
	v_pk_fma_f32 v[50:51], v[98:99], v[190:191], v[50:51]
	s_waitcnt lgkmcnt(10)
	v_pk_fma_f32 v[48:49], v[100:101], v[200:201], v[48:49]
	ds_read_b128 v[248:251], v148 offset:14944
	v_pk_fma_f32 v[50:51], v[102:103], v[202:203], v[50:51]
	ds_read_b128 v[12:15], v148 offset:14960
	v_pk_fma_f32 v[48:49], v[104:105], v[204:205], v[48:49]
	ds_read_b128 v[16:19], v148 offset:14976
	v_pk_fma_f32 v[50:51], v[106:107], v[206:207], v[50:51]
	v_pk_fma_f32 v[48:49], v[108:109], v[208:209], v[48:49]
	v_pk_fma_f32 v[50:51], v[110:111], v[210:211], v[50:51]
	s_waitcnt lgkmcnt(10)
	v_pk_fma_f32 v[48:49], v[112:113], v[212:213], v[48:49]
	ds_read_b128 v[20:23], v148 offset:14992
	v_pk_fma_f32 v[50:51], v[114:115], v[214:215], v[50:51]
	ds_read_b128 v[24:27], v148 offset:15008
	v_pk_fma_f32 v[48:49], v[116:117], v[216:217], v[48:49]
	ds_read_b128 v[28:31], v148 offset:15024
	v_pk_fma_f32 v[50:51], v[118:119], v[218:219], v[50:51]
	v_fma_f32 v48, v120, v220, v48
	v_add_f32_e32 v1, v48, v49
	v_add_f32_e32 v2, v50, v51
	v_sub_f32_e64 v121, -v1, v2
	v_cvt_pk_bf16_f32 v3, v120, v121
	ds_write_b16 v150, v3 offset:8064
	ds_write_b16_d16_hi v150, v3 offset:8208
	s_waitcnt lgkmcnt(12)
	v_fma_f32 v48, v64, v224, v252
	ds_read_b128 v[32:35], v148 offset:15040
	v_mul_f32_e32 v49, v65, v225
	v_pk_mul_f32 v[50:51], v[66:67], v[226:227]
	v_pk_fma_f32 v[48:49], v[68:69], v[228:229], v[48:49]
	v_pk_fma_f32 v[50:51], v[70:71], v[230:231], v[50:51]
	s_waitcnt lgkmcnt(10)
; #define LAS __attribute__((address_space(3)))
; __device__ __forceinline__ bf16_t f2bf(float f) { return (bf16_t)(pk2(f, 0.f) & 0xffffu); }
; template <int I, int C> __device__ __forceinline__ void s2_load(const LAS float* Ll, f32x4 (&lr)[16]) {
;     if constexpr (4 * C < I) { lr[C] = *(const LAS f32x4*)(Ll + I * 64 + 4 * C); s2_load<I, C + 1>(Ll, lr); }
; }
; template <int I, int C> __device__ __forceinline__ void s2_fma(const f32x4 (&lr)[16], const float (&Xc)[64], float& a0, float& a1, float& a2, float& a3) {
;     if constexpr (4 * C < I) {
;         a0 += lr[C].x * Xc[4 * C];
;         if constexpr (4 * C + 1 < I) a1 += lr[C].y * Xc[4 * C + 1];
;         if constexpr (4 * C + 2 < I) a2 += lr[C].z * Xc[4 * C + 2];
;         if constexpr (4 * C + 3 < I) a3 += lr[C].w * Xc[4 * C + 3];
;         s2_fma<I, C + 1>(lr, Xc, a0, a1, a2, a3);
;     }
; }
; template <int I> __device__ __forceinline__ void s2_row(const LAS float* Ll, float (&Xc)[64], int lane) {
;     if constexpr (I < 64) {
;         float a0 = Ll[I * 64 + lane], a1 = 0.f, a2 = 0.f, a3 = 0.f;
;         f32x4 lr[16];
;         s2_load<I, 0>(Ll, lr);
;         s2_fma<I, 0>(lr, Xc, a0, a1, a2, a3);
;         Xc[I] = -((a0 + a1) + (a2 + a3));
;         asm volatile("" ::: "memory");
;         s2_row<I + 1>(Ll, Xc, lane);
;     }
; }
; __device__ __forceinline__ void prep_task(LAS unsigned char* lds, const PrepP& P, int task, int tid, int lane, int wave) {
;     ...
;     if (wave == 0) {
;         float Xc[64];
;         s2_row<0>(Ll, Xc, lane);
; #pragma unroll
;         for (int i = 0; i < 64; ++i) Tl[i * TS + lane] = f2bf(Xc[i]);
;         asm volatile("s_waitcnt lgkmcnt(0)" ::: "memory");
;         Tl[lane * TS + lane] = (bf16_t)0x3F80u;
	v_pk_fma_f32 v[48:49], v[72:73], v[232:233], v[48:49]
	ds_read_b128 v[36:39], v148 offset:15056
	v_pk_fma_f32 v[50:51], v[74:75], v[234:235], v[50:51]
	ds_read_b128 v[128:131], v148 offset:15072
	v_pk_fma_f32 v[48:49], v[76:77], v[236:237], v[48:49]
	ds_read_b128 v[132:135], v148 offset:15104
	v_pk_fma_f32 v[50:51], v[78:79], v[238:239], v[50:51]
	v_pk_fma_f32 v[48:49], v[80:81], v[240:241], v[48:49]
	v_pk_fma_f32 v[50:51], v[82:83], v[242:243], v[50:51]
	s_waitcnt lgkmcnt(10)
	v_pk_fma_f32 v[48:49], v[84:85], v[244:245], v[48:49]
	ds_read_b128 v[136:139], v148 offset:15120
	v_pk_fma_f32 v[50:51], v[86:87], v[246:247], v[50:51]
	ds_read_b128 v[140:143], v148 offset:15136
	v_pk_fma_f32 v[48:49], v[88:89], v[248:249], v[48:49]
	ds_read_b128 v[144:147], v148 offset:15152
	v_pk_fma_f32 v[50:51], v[90:91], v[250:251], v[50:51]
	v_pk_fma_f32 v[48:49], v[92:93], v[12:13], v[48:49]
	v_pk_fma_f32 v[50:51], v[94:95], v[14:15], v[50:51]
	s_waitcnt lgkmcnt(10)
	v_pk_fma_f32 v[48:49], v[96:97], v[16:17], v[48:49]
	ds_read_b128 v[156:159], v148 offset:15168
	v_pk_fma_f32 v[50:51], v[98:99], v[18:19], v[50:51]
	ds_read_b128 v[160:163], v148 offset:15184
	v_pk_fma_f32 v[48:49], v[100:101], v[20:21], v[48:49]
	ds_read_b128 v[164:167], v148 offset:15200
	v_pk_fma_f32 v[50:51], v[102:103], v[22:23], v[50:51]
	v_pk_fma_f32 v[48:49], v[104:105], v[24:25], v[48:49]
	v_pk_fma_f32 v[50:51], v[106:107], v[26:27], v[50:51]
	s_waitcnt lgkmcnt(12)
	v_pk_fma_f32 v[48:49], v[108:109], v[28:29], v[48:49]
	ds_read_b128 v[168:171], v148 offset:15216
	v_pk_fma_f32 v[50:51], v[110:111], v[30:31], v[50:51]
	s_waitcnt lgkmcnt(8)
	v_pk_fma_f32 v[48:49], v[112:113], v[32:33], v[48:49]
	ds_read_b128 v[172:175], v148 offset:15232
	v_pk_fma_f32 v[50:51], v[114:115], v[34:35], v[50:51]
	ds_read_b128 v[176:179], v148 offset:15248
	v_pk_fma_f32 v[48:49], v[116:117], v[36:37], v[48:49]
	ds_read_b128 v[180:183], v148 offset:15264
	v_pk_fma_f32 v[50:51], v[118:119], v[38:39], v[50:51]
	ds_read_b128 v[184:187], v148 offset:15280
	v_pk_fma_f32 v[48:49], v[120:121], v[128:129], v[48:49]
	ds_read_b128 v[188:191], v148 offset:15296
	v_add_f32_e32 v1, v48, v49
	v_add_f32_e32 v2, v50, v51
	v_sub_f32_e64 v122, -v1, v2
	s_waitcnt lgkmcnt(10)
	v_fma_f32 v48, v64, v132, v253
	ds_read_b128 v[200:203], v148 offset:15312
	v_mul_f32_e32 v49, v65, v133
	ds_read_b128 v[204:207], v148 offset:15328
	v_pk_mul_f32 v[50:51], v[66:67], v[134:135]
	ds_read2st64_b32 v[4:5], v149 offset0:60 offset1:61
	v_pk_fma_f32 v[48:49], v[68:69], v[136:137], v[48:49]
	v_pk_fma_f32 v[50:51], v[70:71], v[138:139], v[50:51]
	v_pk_fma_f32 v[48:49], v[72:73], v[140:141], v[48:49]
	v_pk_fma_f32 v[50:51], v[74:75], v[142:143], v[50:51]
	s_waitcnt lgkmcnt(10)
	v_pk_fma_f32 v[48:49], v[76:77], v[144:145], v[48:49]
	ds_read_b128 v[208:211], v148 offset:15360
	v_pk_fma_f32 v[50:51], v[78:79], v[146:147], v[50:51]
	ds_read_b128 v[212:215], v148 offset:15376
	v_pk_fma_f32 v[48:49], v[80:81], v[156:157], v[48:49]
	ds_read_b128 v[216:219], v148 offset:15392
	v_pk_fma_f32 v[50:51], v[82:83], v[158:159], v[50:51]
	v_pk_fma_f32 v[48:49], v[84:85], v[160:161], v[48:49]
	v_pk_fma_f32 v[50:51], v[86:87], v[162:163], v[50:51]
	s_waitcnt lgkmcnt(10)
	v_pk_fma_f32 v[48:49], v[88:89], v[164:165], v[48:49]
	ds_read_b128 v[220:223], v148 offset:15408
	v_pk_fma_f32 v[50:51], v[90:91], v[166:167], v[50:51]
	ds_read_b128 v[224:227], v148 offset:15424
	v_pk_fma_f32 v[48:49], v[92:93], v[168:169], v[48:49]
	ds_read_b128 v[228:231], v148 offset:15440
	v_pk_fma_f32 v[50:51], v[94:95], v[170:171], v[50:51]
	v_pk_fma_f32 v[48:49], v[96:97], v[172:173], v[48:49]
	v_pk_fma_f32 v[50:51], v[98:99], v[174:175], v[50:51]
	s_waitcnt lgkmcnt(10)
	v_pk_fma_f32 v[48:49], v[100:101], v[176:177], v[48:49]
	ds_read_b128 v[232:235], v148 offset:15456
	v_pk_fma_f32 v[50:51], v[102:103], v[178:179], v[50:51]
	ds_read_b128 v[236:239], v148 offset:15472
	v_pk_fma_f32 v[48:49], v[104:105], v[180:181], v[48:49]
	ds_read_b128 v[240:243], v148 offset:15488
	v_pk_fma_f32 v[50:51], v[106:107], v[182:183], v[50:51]
	v_pk_fma_f32 v[48:49], v[108:109], v[184:185], v[48:49]
	v_pk_fma_f32 v[50:51], v[110:111], v[186:187], v[50:51]
	s_waitcnt lgkmcnt(10)
	v_pk_fma_f32 v[48:49], v[112:113], v[188:189], v[48:49]
	ds_read_b128 v[244:247], v148 offset:15504
	v_pk_fma_f32 v[50:51], v[114:115], v[190:191], v[50:51]
	ds_read_b128 v[248:251], v148 offset:15520
	v_pk_fma_f32 v[48:49], v[116:117], v[200:201], v[48:49]
	ds_read_b128 v[12:15], v148 offset:15536
	v_pk_fma_f32 v[50:51], v[118:119], v[202:203], v[50:51]
	v_pk_fma_f32 v[48:49], v[120:121], v[204:205], v[48:49]
	v_fma_f32 v50, v122, v206, v50
	v_add_f32_e32 v1, v48, v49
	v_add_f32_e32 v2, v50, v51
	v_sub_f32_e64 v123, -v1, v2
	v_cvt_pk_bf16_f32 v3, v122, v123
	ds_write_b16 v150, v3 offset:8352
	ds_write_b16_d16_hi v150, v3 offset:8496
	s_waitcnt lgkmcnt(12)
	v_fma_f32 v48, v64, v208, v4
	ds_read_b128 v[16:19], v148 offset:15552
	v_mul_f32_e32 v49, v65, v209
	v_pk_mul_f32 v[50:51], v[66:67], v[210:211]
	v_pk_fma_f32 v[48:49], v[68:69], v[212:213], v[48:49]
	v_pk_fma_f32 v[50:51], v[70:71], v[214:215], v[50:51]
	s_waitcnt lgkmcnt(10)
	v_pk_fma_f32 v[48:49], v[72:73], v[216:217], v[48:49]
	ds_read_b128 v[20:23], v148 offset:15568
	v_pk_fma_f32 v[50:51], v[74:75], v[218:219], v[50:51]
	ds_read_b128 v[24:27], v148 offset:15584
	v_pk_fma_f32 v[48:49], v[76:77], v[220:221], v[48:49]
	ds_read_b128 v[28:31], v148 offset:15616
	v_pk_fma_f32 v[50:51], v[78:79], v[222:223], v[50:51]
	v_pk_fma_f32 v[48:49], v[80:81], v[224:225], v[48:49]
	v_pk_fma_f32 v[50:51], v[82:83], v[226:227], v[50:51]
	s_waitcnt lgkmcnt(10)
; #define LAS __attribute__((address_space(3)))
; __device__ __forceinline__ bf16_t f2bf(float f) { return (bf16_t)(pk2(f, 0.f) & 0xffffu); }
; template <int I, int C> __device__ __forceinline__ void s2_load(const LAS float* Ll, f32x4 (&lr)[16]) {
;     if constexpr (4 * C < I) { lr[C] = *(const LAS f32x4*)(Ll + I * 64 + 4 * C); s2_load<I, C + 1>(Ll, lr); }
; }
; template <int I, int C> __device__ __forceinline__ void s2_fma(const f32x4 (&lr)[16], const float (&Xc)[64], float& a0, float& a1, float& a2, float& a3) {
;     if constexpr (4 * C < I) {
;         a0 += lr[C].x * Xc[4 * C];
;         if constexpr (4 * C + 1 < I) a1 += lr[C].y * Xc[4 * C + 1];
;         if constexpr (4 * C + 2 < I) a2 += lr[C].z * Xc[4 * C + 2];
;         if constexpr (4 * C + 3 < I) a3 += lr[C].w * Xc[4 * C + 3];
;         s2_fma<I, C + 1>(lr, Xc, a0, a1, a2, a3);
;     }
; }
; template <int I> __device__ __forceinline__ void s2_row(const LAS float* Ll, float (&Xc)[64], int lane) {
;     if constexpr (I < 64) {
;         float a0 = Ll[I * 64 + lane], a1 = 0.f, a2 = 0.f, a3 = 0.f;
;         f32x4 lr[16];
;         s2_load<I, 0>(Ll, lr);
;         s2_fma<I, 0>(lr, Xc, a0, a1, a2, a3);
;         Xc[I] = -((a0 + a1) + (a2 + a3));
;         asm volatile("" ::: "memory");
;         s2_row<I + 1>(Ll, Xc, lane);
;     }
; }
; __device__ __forceinline__ void prep_task(LAS unsigned char* lds, const PrepP& P, int task, int tid, int lane, int wave) {
;     ...
;     if (wave == 0) {
;         float Xc[64];
;         s2_row<0>(Ll, Xc, lane);
; #pragma unroll
;         for (int i = 0; i < 64; ++i) Tl[i * TS + lane] = f2bf(Xc[i]);
;         asm volatile("s_waitcnt lgkmcnt(0)" ::: "memory");
;         Tl[lane * TS + lane] = (bf16_t)0x3F80u;
	v_pk_fma_f32 v[48:49], v[84:85], v[228:229], v[48:49]
	ds_read_b128 v[32:35], v148 offset:15632
	v_pk_fma_f32 v[50:51], v[86:87], v[230:231], v[50:51]
	ds_read_b128 v[36:39], v148 offset:15648
	v_pk_fma_f32 v[48:49], v[88:89], v[232:233], v[48:49]
	ds_read_b128 v[128:131], v148 offset:15664
	v_pk_fma_f32 v[50:51], v[90:91], v[234:235], v[50:51]
	v_pk_fma_f32 v[48:49], v[92:93], v[236:237], v[48:49]
	v_pk_fma_f32 v[50:51], v[94:95], v[238:239], v[50:51]
	s_waitcnt lgkmcnt(10)
	v_pk_fma_f32 v[48:49], v[96:97], v[240:241], v[48:49]
	ds_read_b128 v[132:135], v148 offset:15680
	v_pk_fma_f32 v[50:51], v[98:99], v[242:243], v[50:51]
	ds_read_b128 v[136:139], v148 offset:15696
	v_pk_fma_f32 v[48:49], v[100:101], v[244:245], v[48:49]
	ds_read_b128 v[140:143], v148 offset:15712
	v_pk_fma_f32 v[50:51], v[102:103], v[246:247], v[50:51]
	v_pk_fma_f32 v[48:49], v[104:105], v[248:249], v[48:49]
	v_pk_fma_f32 v[50:51], v[106:107], v[250:251], v[50:51]
	s_waitcnt lgkmcnt(12)
	v_pk_fma_f32 v[48:49], v[108:109], v[12:13], v[48:49]
	ds_read_b128 v[144:147], v148 offset:15728
	v_pk_fma_f32 v[50:51], v[110:111], v[14:15], v[50:51]
	s_waitcnt lgkmcnt(8)
	v_pk_fma_f32 v[48:49], v[112:113], v[16:17], v[48:49]
	ds_read_b128 v[156:159], v148 offset:15744
	v_pk_fma_f32 v[50:51], v[114:115], v[18:19], v[50:51]
	ds_read_b128 v[160:163], v148 offset:15760
	v_pk_fma_f32 v[48:49], v[116:117], v[20:21], v[48:49]
	ds_read_b128 v[164:167], v148 offset:15776
	v_pk_fma_f32 v[50:51], v[118:119], v[22:23], v[50:51]
	ds_read_b128 v[168:171], v148 offset:15792
	v_pk_fma_f32 v[48:49], v[120:121], v[24:25], v[48:49]
	ds_read_b128 v[172:175], v148 offset:15808
	v_pk_fma_f32 v[50:51], v[122:123], v[26:27], v[50:51]
	v_add_f32_e32 v1, v48, v49
	v_add_f32_e32 v2, v50, v51
	v_sub_f32_e64 v124, -v1, v2
	s_waitcnt lgkmcnt(10)
	v_fma_f32 v48, v64, v28, v5
	ds_read_b128 v[176:179], v148 offset:15824
	v_mul_f32_e32 v49, v65, v29
	ds_read_b128 v[180:183], v148 offset:15840
	v_pk_mul_f32 v[50:51], v[66:67], v[30:31]
	ds_read_b128 v[184:187], v148 offset:15856
	v_pk_fma_f32 v[48:49], v[68:69], v[32:33], v[48:49]
	v_pk_fma_f32 v[50:51], v[70:71], v[34:35], v[50:51]
	v_pk_fma_f32 v[48:49], v[72:73], v[36:37], v[48:49]
	v_pk_fma_f32 v[50:51], v[74:75], v[38:39], v[50:51]
	s_waitcnt lgkmcnt(10)
	v_pk_fma_f32 v[48:49], v[76:77], v[128:129], v[48:49]
	ds_read2st64_b32 v[6:7], v149 offset0:62 offset1:63
	v_pk_fma_f32 v[50:51], v[78:79], v[130:131], v[50:51]
	ds_read_b128 v[188:191], v148 offset:15872
	v_pk_fma_f32 v[48:49], v[80:81], v[132:133], v[48:49]
	ds_read_b128 v[200:203], v148 offset:15888
	v_pk_fma_f32 v[50:51], v[82:83], v[134:135], v[50:51]
	v_pk_fma_f32 v[48:49], v[84:85], v[136:137], v[48:49]
	v_pk_fma_f32 v[50:51], v[86:87], v[138:139], v[50:51]
	s_waitcnt lgkmcnt(10)
	v_pk_fma_f32 v[48:49], v[88:89], v[140:141], v[48:49]
	ds_read_b128 v[204:207], v148 offset:15904
	v_pk_fma_f32 v[50:51], v[90:91], v[142:143], v[50:51]
	ds_read_b128 v[208:211], v148 offset:15920
	v_pk_fma_f32 v[48:49], v[92:93], v[144:145], v[48:49]
	ds_read_b128 v[212:215], v148 offset:15936
	v_pk_fma_f32 v[50:51], v[94:95], v[146:147], v[50:51]
	v_pk_fma_f32 v[48:49], v[96:97], v[156:157], v[48:49]
	v_pk_fma_f32 v[50:51], v[98:99], v[158:159], v[50:51]
	s_waitcnt lgkmcnt(10)
	v_pk_fma_f32 v[48:49], v[100:101], v[160:161], v[48:49]
	ds_read_b128 v[216:219], v148 offset:15952
	v_pk_fma_f32 v[50:51], v[102:103], v[162:163], v[50:51]
	ds_read_b128 v[220:223], v148 offset:15968
	v_pk_fma_f32 v[48:49], v[104:105], v[164:165], v[48:49]
	ds_read_b128 v[224:227], v148 offset:15984
	v_pk_fma_f32 v[50:51], v[106:107], v[166:167], v[50:51]
	v_pk_fma_f32 v[48:49], v[108:109], v[168:169], v[48:49]
	v_pk_fma_f32 v[50:51], v[110:111], v[170:171], v[50:51]
	s_waitcnt lgkmcnt(10)
	v_pk_fma_f32 v[48:49], v[112:113], v[172:173], v[48:49]
	ds_read_b128 v[228:231], v148 offset:16000
	v_pk_fma_f32 v[50:51], v[114:115], v[174:175], v[50:51]
	ds_read_b128 v[232:235], v148 offset:16016
	v_pk_fma_f32 v[48:49], v[116:117], v[176:177], v[48:49]
	ds_read_b128 v[236:239], v148 offset:16032
	v_pk_fma_f32 v[50:51], v[118:119], v[178:179], v[50:51]
	v_pk_fma_f32 v[48:49], v[120:121], v[180:181], v[48:49]
	v_pk_fma_f32 v[50:51], v[122:123], v[182:183], v[50:51]
	s_waitcnt lgkmcnt(12)
	v_fma_f32 v48, v124, v184, v48
	ds_read_b128 v[240:243], v148 offset:16048
	v_add_f32_e32 v1, v48, v49
	v_add_f32_e32 v2, v50, v51
	v_sub_f32_e64 v125, -v1, v2
	v_cvt_pk_bf16_f32 v3, v124, v125
	ds_write_b16 v150, v3 offset:8640
	ds_write_b16_d16_hi v150, v3 offset:8784
	s_waitcnt lgkmcnt(12)
	v_fma_f32 v48, v64, v188, v6
	ds_read_b128 v[244:247], v148 offset:16064
	v_mul_f32_e32 v49, v65, v189
	v_pk_mul_f32 v[50:51], v[66:67], v[190:191]
	v_pk_fma_f32 v[48:49], v[68:69], v[200:201], v[48:49]
	v_pk_fma_f32 v[50:51], v[70:71], v[202:203], v[50:51]
	s_waitcnt lgkmcnt(10)
; #define LAS __attribute__((address_space(3)))
; __device__ __forceinline__ bf16_t f2bf(float f) { return (bf16_t)(pk2(f, 0.f) & 0xffffu); }
; template <int I, int C> __device__ __forceinline__ void s2_load(const LAS float* Ll, f32x4 (&lr)[16]) {
;     if constexpr (4 * C < I) { lr[C] = *(const LAS f32x4*)(Ll + I * 64 + 4 * C); s2_load<I, C + 1>(Ll, lr); }
; }
; template <int I, int C> __device__ __forceinline__ void s2_fma(const f32x4 (&lr)[16], const float (&Xc)[64], float& a0, float& a1, float& a2, float& a3) {
;     if constexpr (4 * C < I) {
;         a0 += lr[C].x * Xc[4 * C];
;         if constexpr (4 * C + 1 < I) a1 += lr[C].y * Xc[4 * C + 1];
;         if constexpr (4 * C + 2 < I) a2 += lr[C].z * Xc[4 * C + 2];
;         if constexpr (4 * C + 3 < I) a3 += lr[C].w * Xc[4 * C + 3];
;         s2_fma<I, C + 1>(lr, Xc, a0, a1, a2, a3);
;     }
; }
; template <int I> __device__ __forceinline__ void s2_row(const LAS float* Ll, float (&Xc)[64], int lane) {
;     if constexpr (I < 64) {
;         float a0 = Ll[I * 64 + lane], a1 = 0.f, a2 = 0.f, a3 = 0.f;
;         f32x4 lr[16];
;         s2_load<I, 0>(Ll, lr);
;         s2_fma<I, 0>(lr, Xc, a0, a1, a2, a3);
;         Xc[I] = -((a0 + a1) + (a2 + a3));
;         asm volatile("" ::: "memory");
;         s2_row<I + 1>(Ll, Xc, lane);
;     }
; }
; __device__ __forceinline__ void prep_task(LAS unsigned char* lds, const PrepP& P, int task, int tid, int lane, int wave) {
;     ...
;     if (wave == 0) {
;         float Xc[64];
;         s2_row<0>(Ll, Xc, lane);
; #pragma unroll
;         for (int i = 0; i < 64; ++i) Tl[i * TS + lane] = f2bf(Xc[i]);
;         asm volatile("s_waitcnt lgkmcnt(0)" ::: "memory");
;         Tl[lane * TS + lane] = (bf16_t)0x3F80u;
	v_pk_fma_f32 v[48:49], v[72:73], v[204:205], v[48:49]
	ds_read_b128 v[248:251], v148 offset:16080
	v_pk_fma_f32 v[50:51], v[74:75], v[206:207], v[50:51]
	ds_read_b128 v[12:15], v148 offset:16096
	v_pk_fma_f32 v[48:49], v[76:77], v[208:209], v[48:49]
	ds_read_b128 v[16:19], v148 offset:16112
	v_pk_fma_f32 v[50:51], v[78:79], v[210:211], v[50:51]
	v_pk_fma_f32 v[48:49], v[80:81], v[212:213], v[48:49]
	v_pk_fma_f32 v[50:51], v[82:83], v[214:215], v[50:51]
	s_waitcnt lgkmcnt(10)
	v_pk_fma_f32 v[48:49], v[84:85], v[216:217], v[48:49]
	ds_read_b128 v[20:23], v148 offset:16128
	v_pk_fma_f32 v[50:51], v[86:87], v[218:219], v[50:51]
	ds_read_b128 v[24:27], v148 offset:16144
	v_pk_fma_f32 v[48:49], v[88:89], v[220:221], v[48:49]
	ds_read_b128 v[28:31], v148 offset:16160
	v_pk_fma_f32 v[50:51], v[90:91], v[222:223], v[50:51]
	v_pk_fma_f32 v[48:49], v[92:93], v[224:225], v[48:49]
	v_pk_fma_f32 v[50:51], v[94:95], v[226:227], v[50:51]
	s_waitcnt lgkmcnt(10)
	v_pk_fma_f32 v[48:49], v[96:97], v[228:229], v[48:49]
	ds_read_b128 v[32:35], v148 offset:16176
	v_pk_fma_f32 v[50:51], v[98:99], v[230:231], v[50:51]
	ds_read_b128 v[36:39], v148 offset:16192
	v_pk_fma_f32 v[48:49], v[100:101], v[232:233], v[48:49]
	ds_read_b128 v[128:131], v148 offset:16208
	v_pk_fma_f32 v[50:51], v[102:103], v[234:235], v[50:51]
	v_pk_fma_f32 v[48:49], v[104:105], v[236:237], v[48:49]
	v_pk_fma_f32 v[50:51], v[106:107], v[238:239], v[50:51]
	s_waitcnt lgkmcnt(12)
	v_pk_fma_f32 v[48:49], v[108:109], v[240:241], v[48:49]
	ds_read_b128 v[132:135], v148 offset:16224
	v_pk_fma_f32 v[50:51], v[110:111], v[242:243], v[50:51]
	s_waitcnt lgkmcnt(8)
	v_pk_fma_f32 v[48:49], v[112:113], v[244:245], v[48:49]
	ds_read_b128 v[136:139], v148 offset:16240
	v_pk_fma_f32 v[50:51], v[114:115], v[246:247], v[50:51]
	ds_read_b128 v[140:143], v148 offset:16256
	v_pk_fma_f32 v[48:49], v[116:117], v[248:249], v[48:49]
	ds_read_b128 v[144:147], v148 offset:16272
	v_pk_fma_f32 v[50:51], v[118:119], v[250:251], v[50:51]
	ds_read_b128 v[156:159], v148 offset:16288
	v_pk_fma_f32 v[48:49], v[120:121], v[12:13], v[48:49]
	ds_read_b128 v[160:163], v148 offset:16304
	v_pk_fma_f32 v[50:51], v[122:123], v[14:15], v[50:51]
	s_waitcnt lgkmcnt(12)
	v_pk_fma_f32 v[48:49], v[124:125], v[16:17], v[48:49]
	ds_read_b128 v[164:167], v148 offset:16320
	v_add_f32_e32 v1, v48, v49
	v_add_f32_e32 v2, v50, v51
	v_sub_f32_e64 v126, -v1, v2
	s_waitcnt lgkmcnt(10)
	v_fma_f32 v48, v64, v20, v7
	ds_read_b128 v[168:171], v148 offset:16336
	v_mul_f32_e32 v49, v65, v21
	ds_read_b128 v[172:175], v148 offset:16352
	v_pk_mul_f32 v[50:51], v[66:67], v[22:23]
	ds_read_b128 v[176:179], v148 offset:16368
	v_pk_fma_f32 v[48:49], v[68:69], v[24:25], v[48:49]
	v_pk_fma_f32 v[50:51], v[70:71], v[26:27], v[50:51]
	v_pk_fma_f32 v[48:49], v[72:73], v[28:29], v[48:49]
	v_pk_fma_f32 v[50:51], v[74:75], v[30:31], v[50:51]
	s_waitcnt lgkmcnt(10)
	v_pk_fma_f32 v[48:49], v[76:77], v[32:33], v[48:49]
	v_pk_fma_f32 v[50:51], v[78:79], v[34:35], v[50:51]
	v_pk_fma_f32 v[48:49], v[80:81], v[36:37], v[48:49]
	v_pk_fma_f32 v[50:51], v[82:83], v[38:39], v[50:51]
	v_pk_fma_f32 v[48:49], v[84:85], v[128:129], v[48:49]
	v_pk_fma_f32 v[50:51], v[86:87], v[130:131], v[50:51]
	s_waitcnt lgkmcnt(7)
	v_pk_fma_f32 v[48:49], v[88:89], v[132:133], v[48:49]
	v_pk_fma_f32 v[50:51], v[90:91], v[134:135], v[50:51]
	v_pk_fma_f32 v[48:49], v[92:93], v[136:137], v[48:49]
	v_pk_fma_f32 v[50:51], v[94:95], v[138:139], v[50:51]
	v_pk_fma_f32 v[48:49], v[96:97], v[140:141], v[48:49]
	v_pk_fma_f32 v[50:51], v[98:99], v[142:143], v[50:51]
	s_waitcnt lgkmcnt(4)
	v_pk_fma_f32 v[48:49], v[100:101], v[144:145], v[48:49]
	v_pk_fma_f32 v[50:51], v[102:103], v[146:147], v[50:51]
	v_pk_fma_f32 v[48:49], v[104:105], v[156:157], v[48:49]
	v_pk_fma_f32 v[50:51], v[106:107], v[158:159], v[50:51]
	v_pk_fma_f32 v[48:49], v[108:109], v[160:161], v[48:49]
	v_pk_fma_f32 v[50:51], v[110:111], v[162:163], v[50:51]
	s_waitcnt lgkmcnt(1)
	v_pk_fma_f32 v[48:49], v[112:113], v[164:165], v[48:49]
	v_pk_fma_f32 v[50:51], v[114:115], v[166:167], v[50:51]
	v_pk_fma_f32 v[48:49], v[116:117], v[168:169], v[48:49]
	v_pk_fma_f32 v[50:51], v[118:119], v[170:171], v[50:51]
	v_pk_fma_f32 v[48:49], v[120:121], v[172:173], v[48:49]
	v_pk_fma_f32 v[50:51], v[122:123], v[174:175], v[50:51]
	s_waitcnt lgkmcnt(0)
	v_pk_fma_f32 v[48:49], v[124:125], v[176:177], v[48:49]
	v_fma_f32 v50, v126, v178, v50
	v_add_f32_e32 v1, v48, v49
	v_add_f32_e32 v2, v50, v51
	v_sub_f32_e64 v127, -v1, v2
	v_cvt_pk_bf16_f32 v3, v126, v127
	ds_write_b16 v150, v3 offset:8928
	ds_write_b16_d16_hi v150, v3 offset:9072
	s_waitcnt lgkmcnt(0)
	s_movk_i32 s4, 0x92
	v_mad_u32_u24 v1, v56, s4, v0
	v_mov_b32_e32 v2, 0x3f80
	ds_write_b16 v1, v2
	s_branch .LBB0_415
